# adds: P8 per-tile g2 table load batched (3 loads in flight, one wait)
# speedup vs baseline: 1.0543x; 1.0031x over previous
; #define MFMA(a, b, c) __builtin_amdgcn_mfma_f32_32x32x16_bf16((a), (b), (c), 0, 0, 0)
; DI void dma16(const void* src, void* lds_wave_base) { __builtin_amdgcn_global_load_lds((const unsigned*)src, (unsigned*)lds_wave_base, 16, 0, 0); }
; #define WAIT_V(n) asm volatile("s_waitcnt vmcnt(%0)" ::"n"(n) : "memory")
; #define RAW_BARRIER() do { asm volatile("s_waitcnt lgkmcnt(0)" ::: "memory"); __builtin_amdgcn_s_barrier(); } while (0)
; template <typename FA, typename FB, typename FE>
; DI void gemm_tile(char* lds, int K, int astride, int bstride, FA arow, FB brow, FE epi) {
;     ...
;   auto stage = [&](int buf, int kt) {
;     char* sa = lds + buf * 32768;
; #pragma unroll
;     for (int i = 0; i < 2; ++i) {
;       dma16(ap[i] + (size_t)kt * astride, sa + (w * 2 + i) * 1024);
;       dma16(bp[i] + (size_t)kt * bstride, sa + 16384 + (w * 2 + i) * 1024);
;     }
;   };
;   stage(0, 0); stage(1, 1); stage(2, 2);
;   for (int kt = 0; kt < nk; ++kt) {
;     if (kt + 2 < nk) WAIT_V(8); else if (kt + 1 < nk) WAIT_V(4); else WAIT_V(0);
;     RAW_BARRIER();
;     if (kt + 3 < nk) stage((kt + 3) & 3, kt + 3);
;     const char* sa = lds + (kt & 3) * 32768 + wm * 4096;
;     const char* sb = lds + (kt & 3) * 32768 + 16384 + wn * 8192;
; #pragma unroll
;     for (int ks = 0; ks < 2; ++ks) {
;       bf16x8 a0 = *(const bf16x8*)(sa + foff[ks]), a1 = *(const bf16x8*)(sa + 2048 + foff[ks]);
; #pragma unroll
;       for (int nt = 0; nt < 4; ++nt) {
;         bf16x8 bb = *(const bf16x8*)(sb + nt * 2048 + foff[ks]);
;         acc[0][nt] = MFMA(a0, bb, acc[0][nt]);
;         acc[1][nt] = MFMA(a1, bb, acc[1][nt]);
;       }
;     }
; DI void phase_moe(const Params& p, char* lds, int mode) {
;     ...
;       for (int i = tid; i < NBR * 64; i += NT) {
;         const int brr = i >> 6, cc = (i & 63) * 4;
;         *(float4*)(g2t + brr * 256 + cc) = *(const float4*)(mod + brr * 6144 + 5 * 1024 + nt2 * 256 + cc);
;       }
;     }
;     __syncthreads();
.LBB0_427:
	global_load_dwordx4 v[4:7], v[0:1], off
	v_lshl_add_u64 v[0:1], v[0:1], 0, s[50:51]
	global_load_dwordx4 v[248:251], v[0:1], off
	v_lshl_add_u64 v[0:1], v[0:1], 0, s[50:51]
	v_add_u32_e32 v3, 0x400, v3
	s_movk_i32 s1, 0x27f
	v_cmp_ge_u32_e32 vcc, s1, v3
	s_nop 1
	s_and_saveexec_b64 s[6:7], vcc
	global_load_dwordx4 v[252:255], v[0:1], off
	s_or_b64 exec, exec, s[6:7]
	s_waitcnt vmcnt(0)
	ds_write_b128 v2, v[4:7]
	ds_write_b128 v2, v[248:251] offset:8192
	s_and_saveexec_b64 s[6:7], vcc
	ds_write_b128 v2, v[252:255] offset:16384
	s_or_b64 exec, exec, s[6:7]
	s_mov_b64 s[6:7], 0
	s_or_b64 exec, exec, s[6:7]
	s_lshl_b32 s8, s48, 2
	s_add_i32 s8, s8, 0x25e00
	v_mov_b32_e32 v0, s8
	s_waitcnt lgkmcnt(0)
	s_barrier
	ds_read_b32 v0, v0
	v_readfirstlane_b32 s6, v186
	s_lshr_b32 s7, s6, 6
	v_lshl_or_b32 v4, s7, 5, v188
	s_mov_b32 s5, s49
	s_waitcnt lgkmcnt(0)
	v_add_u32_e32 v5, v0, v153
	v_add_u32_e32 v2, v4, v5
	v_min_i32_e32 v2, 0x2ffff, v2
	v_ashrrev_i32_e32 v3, 31, v2
	v_lshlrev_b64 v[2:3], 6, v[2:3]
	v_lshl_add_u64 v[136:137], v[130:131], 0, v[2:3]
	v_add_u32_e32 v2, s0, v4
	s_lshl_b64 s[4:5], s[4:5], 20
	v_ashrrev_i32_e32 v3, 31, v2
	v_lshl_add_u64 v[0:1], v[132:133], 0, s[4:5]
	v_lshlrev_b64 v[2:3], 6, v[2:3]
	v_or_b32_e32 v4, 16, v4
	v_lshl_add_u64 v[138:139], v[0:1], 0, v[2:3]
	v_add_u32_e32 v2, v4, v5
	v_min_i32_e32 v2, 0x2ffff, v2
	v_ashrrev_i32_e32 v3, 31, v2
	v_lshlrev_b64 v[2:3], 6, v[2:3]
	s_lshl_b32 s17, s7, 11
	v_lshl_add_u64 v[140:141], v[130:131], 0, v[2:3]
	v_add_u32_e32 v2, s0, v4
	s_mov_b32 m0, s17
	s_add_i32 s18, s17, 0x4000
	v_ashrrev_i32_e32 v3, 31, v2
	global_load_lds_dwordx4 v[136:137], off
	s_mov_b32 m0, s18
	s_or_b32 s19, s17, 0x400
	v_lshlrev_b64 v[2:3], 6, v[2:3]
	global_load_lds_dwordx4 v[138:139], off
	s_mov_b32 m0, s19
	s_add_i32 s20, s17, 0x4400
	s_lshr_b32 s1, s6, 7
	v_lshl_add_u64 v[142:143], v[0:1], 0, v[2:3]
	s_bfe_u32 s4, s6, 0x10006
	global_load_lds_dwordx4 v[140:141], off
	s_mov_b32 m0, s20
	s_mov_b64 s[6:7], 0xc00000
	s_add_i32 s13, s17, 0x8000
	global_load_lds_dwordx4 v[142:143], off
	v_lshl_add_u64 v[0:1], v[136:137], 0, s[6:7]
	s_mov_b32 m0, s13
	s_mov_b64 s[8:9], 0x10000
	s_add_i32 s14, s17, 0xc000
	global_load_lds_dwordx4 v[0:1], off
	v_lshl_add_u64 v[0:1], v[138:139], 0, s[8:9]
	s_mov_b32 m0, s14
	s_add_i32 s15, s17, 0x8400
	global_load_lds_dwordx4 v[0:1], off
	v_lshl_add_u64 v[0:1], v[140:141], 0, s[6:7]
	s_mov_b32 m0, s15
	s_add_i32 s16, s17, 0xc400
	global_load_lds_dwordx4 v[0:1], off
	v_lshl_add_u64 v[0:1], v[142:143], 0, s[8:9]
	s_mov_b32 m0, s16
	s_mov_b64 s[6:7], 0x1800000
	s_add_i32 s9, s17, 0x10000
	global_load_lds_dwordx4 v[0:1], off
	v_lshl_add_u64 v[0:1], v[136:137], 0, s[6:7]
	s_mov_b32 m0, s9
	s_mov_b64 s[22:23], 0x20000
	s_add_i32 s10, s17, 0x14000
	global_load_lds_dwordx4 v[0:1], off
	v_lshl_add_u64 v[0:1], v[138:139], 0, s[22:23]
	s_mov_b32 m0, s10
	s_add_i32 s11, s17, 0x10400
	global_load_lds_dwordx4 v[0:1], off
	v_lshl_add_u64 v[0:1], v[140:141], 0, s[6:7]
	s_mov_b32 m0, s11
	s_add_i32 s12, s17, 0x14400
	global_load_lds_dwordx4 v[0:1], off
	v_lshl_add_u64 v[0:1], v[142:143], 0, s[22:23]
	s_mov_b32 m0, s12
	s_mov_b64 s[24:25], 0x2400000
	global_load_lds_dwordx4 v[0:1], off
	s_add_i32 s5, s17, 0x18000
	s_waitcnt vmcnt(8)
	v_lshl_add_u64 v[0:1], v[136:137], 0, s[24:25]
	s_mov_b32 m0, s5
	s_add_i32 s6, s17, 0x1c000
	s_waitcnt lgkmcnt(0)
	s_barrier
	global_load_lds_dwordx4 v[0:1], off
	v_lshl_add_u64 v[0:1], v[138:139], 0, s[50:51]
	s_mov_b32 m0, s6
	s_add_i32 s7, s17, 0x18400
	global_load_lds_dwordx4 v[0:1], off
	v_lshl_add_u64 v[0:1], v[140:141], 0, s[24:25]
	s_mov_b32 m0, s7
	s_add_i32 s8, s17, 0x1c400
	s_lshl_b32 s21, s1, 12
	s_lshl_b32 s22, s4, 13
	global_load_lds_dwordx4 v[0:1], off
	v_lshl_add_u64 v[0:1], v[142:143], 0, s[50:51]
	s_mov_b32 m0, s8
	v_or_b32_e32 v128, s21, v189
	global_load_lds_dwordx4 v[0:1], off
	v_or_b32_e32 v144, s22, v189
	ds_read_b128 v[0:3], v128
	ds_read_b128 v[4:7], v128 offset:2048
	ds_read_b128 v[8:11], v144 offset:16384
	s_waitcnt lgkmcnt(0)
	v_mfma_f32_32x32x16_bf16 v[112:127], v[0:3], v[8:11], 0
	v_or_b32_e32 v147, s21, v190
	v_or_b32_e32 v148, s22, v190
	s_mov_b64 s[24:25], 0x3000000
	v_lshl_add_u64 v[150:151], v[136:137], 0, s[24:25]
	s_mov_b32 m0, s17
	s_mov_b64 s[26:27], 0x40000
	s_add_i32 s23, s21, 0x10000
	v_mfma_f32_32x32x16_bf16 v[48:63], v[4:7], v[8:11], 0
	ds_read_b128 v[8:11], v144 offset:18432
	v_or_b32_e32 v149, s23, v189
	s_add_i32 s21, s21, 0x18000
	v_or_b32_e32 v146, s21, v189
	v_or_b32_e32 v152, s21, v190
	s_waitcnt lgkmcnt(0)
	v_mfma_f32_32x32x16_bf16 v[96:111], v[0:3], v[8:11], 0
	v_mfma_f32_32x32x16_bf16 v[32:47], v[4:7], v[8:11], 0
	ds_read_b128 v[8:11], v144 offset:20480
	s_waitcnt lgkmcnt(0)
	v_mfma_f32_32x32x16_bf16 v[80:95], v[0:3], v[8:11], 0
	v_mfma_f32_32x32x16_bf16 v[16:31], v[4:7], v[8:11], 0
	ds_read_b128 v[8:11], v144 offset:22528
	ds_read_b128 v[154:157], v147
	ds_read_b128 v[158:161], v147 offset:2048
	ds_read_b128 v[162:165], v148 offset:16384
	s_waitcnt lgkmcnt(0)
	v_mfma_f32_32x32x16_bf16 v[112:127], v[154:157], v[162:165], v[112:127]
	v_mfma_f32_32x32x16_bf16 v[48:63], v[158:161], v[162:165], v[48:63]
	ds_read_b128 v[162:165], v148 offset:18432
	s_waitcnt lgkmcnt(0)
	v_mfma_f32_32x32x16_bf16 v[96:111], v[154:157], v[162:165], v[96:111]
	v_mfma_f32_32x32x16_bf16 v[32:47], v[158:161], v[162:165], v[32:47]
	ds_read_b128 v[162:165], v148 offset:20480
	v_mfma_f32_32x32x16_bf16 v[64:79], v[0:3], v[8:11], 0
	v_mfma_f32_32x32x16_bf16 v[0:15], v[4:7], v[8:11], 0
	s_waitcnt lgkmcnt(0)
	v_mfma_f32_32x32x16_bf16 v[80:95], v[154:157], v[162:165], v[80:95]
	v_mfma_f32_32x32x16_bf16 v[16:31], v[158:161], v[162:165], v[16:31]
	ds_read_b128 v[162:165], v148 offset:22528
	s_waitcnt vmcnt(8)
	s_waitcnt lgkmcnt(0)
	s_barrier
; #define MFMA(a, b, c) __builtin_amdgcn_mfma_f32_32x32x16_bf16((a), (b), (c), 0, 0, 0)
; #define WAIT_V(n) asm volatile("s_waitcnt vmcnt(%0)" ::"n"(n) : "memory")
; #define RAW_BARRIER() do { asm volatile("s_waitcnt lgkmcnt(0)" ::: "memory"); __builtin_amdgcn_s_barrier(); } while (0)
; template <typename FA, typename FB, typename FE>
; DI void gemm_tile(char* lds, int K, int astride, int bstride, FA arow, FB brow, FE epi) {
;     ...
;   for (int kt = 0; kt < nk; ++kt) {
;     if (kt + 2 < nk) WAIT_V(8); else if (kt + 1 < nk) WAIT_V(4); else WAIT_V(0);
;     RAW_BARRIER();
;     if (kt + 3 < nk) stage((kt + 3) & 3, kt + 3);
;     const char* sa = lds + (kt & 3) * 32768 + wm * 4096;
;     const char* sb = lds + (kt & 3) * 32768 + 16384 + wn * 8192;
; #pragma unroll
;     for (int ks = 0; ks < 2; ++ks) {
;       bf16x8 a0 = *(const bf16x8*)(sa + foff[ks]), a1 = *(const bf16x8*)(sa + 2048 + foff[ks]);
; #pragma unroll
;       for (int nt = 0; nt < 4; ++nt) {
;         bf16x8 bb = *(const bf16x8*)(sb + nt * 2048 + foff[ks]);
;         acc[0][nt] = MFMA(a0, bb, acc[0][nt]);
;         acc[1][nt] = MFMA(a1, bb, acc[1][nt]);
;       }
;     }
	global_load_lds_dwordx4 v[150:151], off
	v_lshl_add_u64 v[150:151], v[138:139], 0, s[26:27]
	s_mov_b32 m0, s18
	s_waitcnt lgkmcnt(0)
	v_mfma_f32_32x32x16_bf16 v[64:79], v[154:157], v[162:165], v[64:79]
	global_load_lds_dwordx4 v[150:151], off
	v_lshl_add_u64 v[150:151], v[140:141], 0, s[24:25]
	s_mov_b32 m0, s19
	s_mov_b64 s[24:25], 0x3c00000
	global_load_lds_dwordx4 v[150:151], off
	v_lshl_add_u64 v[150:151], v[142:143], 0, s[26:27]
	s_mov_b32 m0, s20
	v_mfma_f32_32x32x16_bf16 v[0:15], v[158:161], v[162:165], v[0:15]
	global_load_lds_dwordx4 v[150:151], off
	ds_read_b128 v[154:157], v128 offset:32768
	ds_read_b128 v[158:161], v128 offset:34816
	ds_read_b128 v[162:165], v144 offset:49152
	v_lshl_add_u64 v[150:151], v[136:137], 0, s[24:25]
	s_mov_b32 m0, s13
	s_mov_b64 s[26:27], 0x50000
	s_waitcnt lgkmcnt(0)
	v_mfma_f32_32x32x16_bf16 v[112:127], v[154:157], v[162:165], v[112:127]
	v_mfma_f32_32x32x16_bf16 v[48:63], v[158:161], v[162:165], v[48:63]
	ds_read_b128 v[162:165], v144 offset:51200
	s_waitcnt lgkmcnt(0)
	v_mfma_f32_32x32x16_bf16 v[96:111], v[154:157], v[162:165], v[96:111]
	v_mfma_f32_32x32x16_bf16 v[32:47], v[158:161], v[162:165], v[32:47]
	ds_read_b128 v[162:165], v144 offset:53248
	s_waitcnt lgkmcnt(0)
	v_mfma_f32_32x32x16_bf16 v[80:95], v[154:157], v[162:165], v[80:95]
	v_mfma_f32_32x32x16_bf16 v[16:31], v[158:161], v[162:165], v[16:31]
	ds_read_b128 v[162:165], v144 offset:55296
	s_waitcnt lgkmcnt(0)
	v_mfma_f32_32x32x16_bf16 v[64:79], v[154:157], v[162:165], v[64:79]
	v_mfma_f32_32x32x16_bf16 v[0:15], v[158:161], v[162:165], v[0:15]
	ds_read_b128 v[154:157], v147 offset:32768
	ds_read_b128 v[158:161], v147 offset:34816
	ds_read_b128 v[162:165], v148 offset:49152
	s_waitcnt lgkmcnt(0)
	v_mfma_f32_32x32x16_bf16 v[112:127], v[154:157], v[162:165], v[112:127]
	v_mfma_f32_32x32x16_bf16 v[48:63], v[158:161], v[162:165], v[48:63]
	ds_read_b128 v[162:165], v148 offset:51200
	s_waitcnt lgkmcnt(0)
	v_mfma_f32_32x32x16_bf16 v[96:111], v[154:157], v[162:165], v[96:111]
	v_mfma_f32_32x32x16_bf16 v[32:47], v[158:161], v[162:165], v[32:47]
	ds_read_b128 v[162:165], v148 offset:53248
	s_waitcnt lgkmcnt(0)
	v_mfma_f32_32x32x16_bf16 v[80:95], v[154:157], v[162:165], v[80:95]
	v_mfma_f32_32x32x16_bf16 v[16:31], v[158:161], v[162:165], v[16:31]
	ds_read_b128 v[162:165], v148 offset:55296
	s_waitcnt vmcnt(8)
	s_waitcnt lgkmcnt(0)
	s_barrier
	global_load_lds_dwordx4 v[150:151], off
	v_lshl_add_u64 v[150:151], v[138:139], 0, s[26:27]
	s_mov_b32 m0, s14
	s_waitcnt lgkmcnt(0)
	v_mfma_f32_32x32x16_bf16 v[64:79], v[154:157], v[162:165], v[64:79]
	global_load_lds_dwordx4 v[150:151], off
	v_lshl_add_u64 v[150:151], v[140:141], 0, s[24:25]
	s_mov_b32 m0, s15
	s_or_b32 s24, s22, 0x14000
	global_load_lds_dwordx4 v[150:151], off
	v_lshl_add_u64 v[150:151], v[142:143], 0, s[26:27]
	s_mov_b32 m0, s16
	v_mfma_f32_32x32x16_bf16 v[0:15], v[158:161], v[162:165], v[0:15]
	global_load_lds_dwordx4 v[150:151], off
	v_or_b32_e32 v151, s24, v189
	ds_read_b128 v[154:157], v149
	ds_read_b128 v[158:161], v149 offset:2048
	ds_read_b128 v[162:165], v151
	s_mov_b32 m0, s9
	s_or_b32 s22, s22, 0x1c000
	s_waitcnt lgkmcnt(0)
	v_mfma_f32_32x32x16_bf16 v[112:127], v[154:157], v[162:165], v[112:127]
	v_or_b32_e32 v150, s22, v189
	v_mfma_f32_32x32x16_bf16 v[48:63], v[158:161], v[162:165], v[48:63]
	ds_read_b128 v[162:165], v151 offset:2048
	s_waitcnt lgkmcnt(0)
	v_mfma_f32_32x32x16_bf16 v[96:111], v[154:157], v[162:165], v[96:111]
	v_mfma_f32_32x32x16_bf16 v[32:47], v[158:161], v[162:165], v[32:47]
	ds_read_b128 v[162:165], v151 offset:4096
	s_waitcnt lgkmcnt(0)
	v_mfma_f32_32x32x16_bf16 v[80:95], v[154:157], v[162:165], v[80:95]
	v_mfma_f32_32x32x16_bf16 v[16:31], v[158:161], v[162:165], v[16:31]
	ds_read_b128 v[162:165], v151 offset:6144
	s_waitcnt lgkmcnt(0)
	v_mfma_f32_32x32x16_bf16 v[64:79], v[154:157], v[162:165], v[64:79]
	v_or_b32_e32 v155, s23, v190
	v_or_b32_e32 v156, s24, v190
	v_or_b32_e32 v154, s22, v190
	v_mfma_f32_32x32x16_bf16 v[0:15], v[158:161], v[162:165], v[0:15]
	ds_read_b128 v[158:161], v155
	ds_read_b128 v[162:165], v155 offset:2048
	ds_read_b128 v[166:169], v156
	s_waitcnt lgkmcnt(0)
	v_mfma_f32_32x32x16_bf16 v[112:127], v[158:161], v[166:169], v[112:127]
	v_mfma_f32_32x32x16_bf16 v[48:63], v[162:165], v[166:169], v[48:63]
	ds_read_b128 v[166:169], v156 offset:2048
	s_waitcnt lgkmcnt(0)
	v_mfma_f32_32x32x16_bf16 v[96:111], v[158:161], v[166:169], v[96:111]
	v_mfma_f32_32x32x16_bf16 v[32:47], v[162:165], v[166:169], v[32:47]
	ds_read_b128 v[166:169], v156 offset:4096
	s_waitcnt lgkmcnt(0)
	v_mfma_f32_32x32x16_bf16 v[80:95], v[158:161], v[166:169], v[80:95]
	v_mfma_f32_32x32x16_bf16 v[16:31], v[162:165], v[166:169], v[16:31]
	ds_read_b128 v[166:169], v156 offset:6144
	s_waitcnt vmcnt(8)
	s_waitcnt lgkmcnt(0)
	s_barrier
; #define MFMA(a, b, c) __builtin_amdgcn_mfma_f32_32x32x16_bf16((a), (b), (c), 0, 0, 0)
; #define WAIT_V(n) asm volatile("s_waitcnt vmcnt(%0)" ::"n"(n) : "memory")
; #define RAW_BARRIER() do { asm volatile("s_waitcnt lgkmcnt(0)" ::: "memory"); __builtin_amdgcn_s_barrier(); } while (0)
; template <typename FA, typename FB, typename FE>
; DI void gemm_tile(char* lds, int K, int astride, int bstride, FA arow, FB brow, FE epi) {
;     ...
;   for (int kt = 0; kt < nk; ++kt) {
;     if (kt + 2 < nk) WAIT_V(8); else if (kt + 1 < nk) WAIT_V(4); else WAIT_V(0);
;     RAW_BARRIER();
;     if (kt + 3 < nk) stage((kt + 3) & 3, kt + 3);
;     const char* sa = lds + (kt & 3) * 32768 + wm * 4096;
;     const char* sb = lds + (kt & 3) * 32768 + 16384 + wn * 8192;
; #pragma unroll
;     for (int ks = 0; ks < 2; ++ks) {
;       bf16x8 a0 = *(const bf16x8*)(sa + foff[ks]), a1 = *(const bf16x8*)(sa + 2048 + foff[ks]);
; #pragma unroll
;       for (int nt = 0; nt < 4; ++nt) {
;         bf16x8 bb = *(const bf16x8*)(sb + nt * 2048 + foff[ks]);
;         acc[0][nt] = MFMA(a0, bb, acc[0][nt]);
;         acc[1][nt] = MFMA(a1, bb, acc[1][nt]);
;       }
;     }
	s_waitcnt lgkmcnt(0)
	v_mfma_f32_32x32x16_bf16 v[64:79], v[158:161], v[166:169], v[64:79]
	v_lshl_add_u64 v[158:159], v[136:137], 0, s[70:71]
	global_load_lds_dwordx4 v[158:159], off
	v_lshl_add_u64 v[158:159], v[138:139], 0, s[68:69]
	s_mov_b32 m0, s10
	s_nop 0
	global_load_lds_dwordx4 v[158:159], off
	v_lshl_add_u64 v[158:159], v[140:141], 0, s[70:71]
	s_mov_b32 m0, s11
	v_mfma_f32_32x32x16_bf16 v[0:15], v[162:165], v[166:169], v[0:15]
	global_load_lds_dwordx4 v[158:159], off
	v_lshl_add_u64 v[158:159], v[142:143], 0, s[68:69]
	s_mov_b32 m0, s12
	s_nop 0
	global_load_lds_dwordx4 v[158:159], off
	ds_read_b128 v[158:161], v146
	ds_read_b128 v[162:165], v146 offset:2048
	ds_read_b128 v[166:169], v150
	s_waitcnt lgkmcnt(0)
	v_mfma_f32_32x32x16_bf16 v[112:127], v[158:161], v[166:169], v[112:127]
	s_mov_b32 m0, s5
	v_mfma_f32_32x32x16_bf16 v[48:63], v[162:165], v[166:169], v[48:63]
	ds_read_b128 v[166:169], v150 offset:2048
	s_waitcnt lgkmcnt(0)
	v_mfma_f32_32x32x16_bf16 v[96:111], v[158:161], v[166:169], v[96:111]
	v_mfma_f32_32x32x16_bf16 v[32:47], v[162:165], v[166:169], v[32:47]
	ds_read_b128 v[166:169], v150 offset:4096
	s_waitcnt lgkmcnt(0)
	v_mfma_f32_32x32x16_bf16 v[80:95], v[158:161], v[166:169], v[80:95]
	v_mfma_f32_32x32x16_bf16 v[16:31], v[162:165], v[166:169], v[16:31]
	ds_read_b128 v[166:169], v150 offset:6144
	s_waitcnt lgkmcnt(0)
	v_mfma_f32_32x32x16_bf16 v[64:79], v[158:161], v[166:169], v[64:79]
	v_mfma_f32_32x32x16_bf16 v[0:15], v[162:165], v[166:169], v[0:15]
	ds_read_b128 v[158:161], v152
	ds_read_b128 v[162:165], v152 offset:2048
	ds_read_b128 v[166:169], v154
	s_waitcnt lgkmcnt(0)
	v_mfma_f32_32x32x16_bf16 v[112:127], v[158:161], v[166:169], v[112:127]
	v_mfma_f32_32x32x16_bf16 v[48:63], v[162:165], v[166:169], v[48:63]
	ds_read_b128 v[166:169], v154 offset:2048
	s_waitcnt lgkmcnt(0)
	v_mfma_f32_32x32x16_bf16 v[96:111], v[158:161], v[166:169], v[96:111]
	v_mfma_f32_32x32x16_bf16 v[32:47], v[162:165], v[166:169], v[32:47]
	ds_read_b128 v[166:169], v154 offset:4096
	s_waitcnt lgkmcnt(0)
	v_mfma_f32_32x32x16_bf16 v[80:95], v[158:161], v[166:169], v[80:95]
	v_mfma_f32_32x32x16_bf16 v[16:31], v[162:165], v[166:169], v[16:31]
	ds_read_b128 v[166:169], v154 offset:6144
	s_waitcnt vmcnt(8)
	s_waitcnt lgkmcnt(0)
	s_barrier
	s_waitcnt lgkmcnt(0)
	v_mfma_f32_32x32x16_bf16 v[64:79], v[158:161], v[166:169], v[64:79]
	v_lshl_add_u64 v[158:159], v[136:137], 0, s[74:75]
	global_load_lds_dwordx4 v[158:159], off
	v_lshl_add_u64 v[158:159], v[138:139], 0, s[76:77]
	s_mov_b32 m0, s6
	s_nop 0
	global_load_lds_dwordx4 v[158:159], off
	v_lshl_add_u64 v[158:159], v[140:141], 0, s[74:75]
	s_mov_b32 m0, s7
	v_mfma_f32_32x32x16_bf16 v[0:15], v[162:165], v[166:169], v[0:15]
	global_load_lds_dwordx4 v[158:159], off
	v_lshl_add_u64 v[158:159], v[142:143], 0, s[76:77]
	s_mov_b32 m0, s8
	s_nop 0
	global_load_lds_dwordx4 v[158:159], off
	ds_read_b128 v[158:161], v128
	ds_read_b128 v[162:165], v128 offset:2048
	ds_read_b128 v[166:169], v144 offset:16384
	s_waitcnt lgkmcnt(0)
	v_mfma_f32_32x32x16_bf16 v[112:127], v[158:161], v[166:169], v[112:127]
	s_mov_b32 m0, s17
	v_mfma_f32_32x32x16_bf16 v[48:63], v[162:165], v[166:169], v[48:63]
	ds_read_b128 v[166:169], v144 offset:18432
	s_waitcnt lgkmcnt(0)
	v_mfma_f32_32x32x16_bf16 v[96:111], v[158:161], v[166:169], v[96:111]
	v_mfma_f32_32x32x16_bf16 v[32:47], v[162:165], v[166:169], v[32:47]
	ds_read_b128 v[166:169], v144 offset:20480
	s_waitcnt lgkmcnt(0)
	v_mfma_f32_32x32x16_bf16 v[80:95], v[158:161], v[166:169], v[80:95]
	v_mfma_f32_32x32x16_bf16 v[16:31], v[162:165], v[166:169], v[16:31]
	ds_read_b128 v[166:169], v144 offset:22528
	s_waitcnt lgkmcnt(0)
	v_mfma_f32_32x32x16_bf16 v[64:79], v[158:161], v[166:169], v[64:79]
	v_mfma_f32_32x32x16_bf16 v[0:15], v[162:165], v[166:169], v[0:15]
	ds_read_b128 v[158:161], v147
	ds_read_b128 v[162:165], v147 offset:2048
	ds_read_b128 v[166:169], v148 offset:16384
	s_waitcnt lgkmcnt(0)
	v_mfma_f32_32x32x16_bf16 v[112:127], v[158:161], v[166:169], v[112:127]
	v_mfma_f32_32x32x16_bf16 v[48:63], v[162:165], v[166:169], v[48:63]
	ds_read_b128 v[166:169], v148 offset:18432
	s_waitcnt lgkmcnt(0)
	v_mfma_f32_32x32x16_bf16 v[96:111], v[158:161], v[166:169], v[96:111]
	v_mfma_f32_32x32x16_bf16 v[32:47], v[162:165], v[166:169], v[32:47]
	ds_read_b128 v[166:169], v148 offset:20480
	s_waitcnt lgkmcnt(0)
	v_mfma_f32_32x32x16_bf16 v[80:95], v[158:161], v[166:169], v[80:95]
	v_mfma_f32_32x32x16_bf16 v[16:31], v[162:165], v[166:169], v[16:31]
	ds_read_b128 v[166:169], v148 offset:22528
	s_waitcnt vmcnt(8)
	s_waitcnt lgkmcnt(0)
	s_barrier
; #define MFMA(a, b, c) __builtin_amdgcn_mfma_f32_32x32x16_bf16((a), (b), (c), 0, 0, 0)
; #define WAIT_V(n) asm volatile("s_waitcnt vmcnt(%0)" ::"n"(n) : "memory")
; #define RAW_BARRIER() do { asm volatile("s_waitcnt lgkmcnt(0)" ::: "memory"); __builtin_amdgcn_s_barrier(); } while (0)
; template <typename FA, typename FB, typename FE>
; DI void gemm_tile(char* lds, int K, int astride, int bstride, FA arow, FB brow, FE epi) {
;     ...
;   for (int kt = 0; kt < nk; ++kt) {
;     if (kt + 2 < nk) WAIT_V(8); else if (kt + 1 < nk) WAIT_V(4); else WAIT_V(0);
;     RAW_BARRIER();
;     if (kt + 3 < nk) stage((kt + 3) & 3, kt + 3);
;     const char* sa = lds + (kt & 3) * 32768 + wm * 4096;
;     const char* sb = lds + (kt & 3) * 32768 + 16384 + wn * 8192;
; #pragma unroll
;     for (int ks = 0; ks < 2; ++ks) {
;       bf16x8 a0 = *(const bf16x8*)(sa + foff[ks]), a1 = *(const bf16x8*)(sa + 2048 + foff[ks]);
; #pragma unroll
;       for (int nt = 0; nt < 4; ++nt) {
;         bf16x8 bb = *(const bf16x8*)(sb + nt * 2048 + foff[ks]);
;         acc[0][nt] = MFMA(a0, bb, acc[0][nt]);
;         acc[1][nt] = MFMA(a1, bb, acc[1][nt]);
;       }
;     }
	s_waitcnt lgkmcnt(0)
	v_mfma_f32_32x32x16_bf16 v[64:79], v[158:161], v[166:169], v[64:79]
	v_lshl_add_u64 v[158:159], v[136:137], 0, s[78:79]
	global_load_lds_dwordx4 v[158:159], off
	v_lshl_add_u64 v[158:159], v[138:139], 0, s[80:81]
	s_mov_b32 m0, s18
	s_nop 0
	global_load_lds_dwordx4 v[158:159], off
	v_lshl_add_u64 v[158:159], v[140:141], 0, s[78:79]
	s_mov_b32 m0, s19
	v_mfma_f32_32x32x16_bf16 v[0:15], v[162:165], v[166:169], v[0:15]
	global_load_lds_dwordx4 v[158:159], off
	v_lshl_add_u64 v[158:159], v[142:143], 0, s[80:81]
	s_mov_b32 m0, s20
	s_nop 0
	global_load_lds_dwordx4 v[158:159], off
	ds_read_b128 v[158:161], v128 offset:32768
	ds_read_b128 v[162:165], v128 offset:34816
	ds_read_b128 v[166:169], v144 offset:49152
	s_waitcnt lgkmcnt(0)
	v_mfma_f32_32x32x16_bf16 v[112:127], v[158:161], v[166:169], v[112:127]
	s_mov_b32 m0, s13
	v_mfma_f32_32x32x16_bf16 v[48:63], v[162:165], v[166:169], v[48:63]
	ds_read_b128 v[166:169], v144 offset:51200
	s_waitcnt lgkmcnt(0)
	v_mfma_f32_32x32x16_bf16 v[96:111], v[158:161], v[166:169], v[96:111]
	v_mfma_f32_32x32x16_bf16 v[32:47], v[162:165], v[166:169], v[32:47]
	ds_read_b128 v[166:169], v144 offset:53248
	s_waitcnt lgkmcnt(0)
	v_mfma_f32_32x32x16_bf16 v[80:95], v[158:161], v[166:169], v[80:95]
	v_mfma_f32_32x32x16_bf16 v[16:31], v[162:165], v[166:169], v[16:31]
	ds_read_b128 v[166:169], v144 offset:55296
	s_waitcnt lgkmcnt(0)
	v_mfma_f32_32x32x16_bf16 v[64:79], v[158:161], v[166:169], v[64:79]
	v_mfma_f32_32x32x16_bf16 v[0:15], v[162:165], v[166:169], v[0:15]
	ds_read_b128 v[158:161], v147 offset:32768
	ds_read_b128 v[162:165], v147 offset:34816
	ds_read_b128 v[166:169], v148 offset:49152
	s_waitcnt lgkmcnt(0)
	v_mfma_f32_32x32x16_bf16 v[112:127], v[158:161], v[166:169], v[112:127]
	v_mfma_f32_32x32x16_bf16 v[48:63], v[162:165], v[166:169], v[48:63]
	ds_read_b128 v[166:169], v148 offset:51200
	s_waitcnt lgkmcnt(0)
	v_mfma_f32_32x32x16_bf16 v[96:111], v[158:161], v[166:169], v[96:111]
	v_mfma_f32_32x32x16_bf16 v[32:47], v[162:165], v[166:169], v[32:47]
	ds_read_b128 v[166:169], v148 offset:53248
	s_waitcnt lgkmcnt(0)
	v_mfma_f32_32x32x16_bf16 v[80:95], v[158:161], v[166:169], v[80:95]
	v_mfma_f32_32x32x16_bf16 v[16:31], v[162:165], v[166:169], v[16:31]
	ds_read_b128 v[166:169], v148 offset:55296
	s_waitcnt vmcnt(8)
	s_waitcnt lgkmcnt(0)
	s_barrier
	s_waitcnt lgkmcnt(0)
	v_mfma_f32_32x32x16_bf16 v[64:79], v[158:161], v[166:169], v[64:79]
	v_lshl_add_u64 v[158:159], v[136:137], 0, s[82:83]
	global_load_lds_dwordx4 v[158:159], off
	v_lshl_add_u64 v[158:159], v[138:139], 0, s[84:85]
	s_mov_b32 m0, s14
	s_nop 0
	global_load_lds_dwordx4 v[158:159], off
	v_lshl_add_u64 v[158:159], v[140:141], 0, s[82:83]
	s_mov_b32 m0, s15
	v_mfma_f32_32x32x16_bf16 v[0:15], v[162:165], v[166:169], v[0:15]
	global_load_lds_dwordx4 v[158:159], off
	v_lshl_add_u64 v[158:159], v[142:143], 0, s[84:85]
	s_mov_b32 m0, s16
	s_nop 0
	global_load_lds_dwordx4 v[158:159], off
	ds_read_b128 v[158:161], v149
	ds_read_b128 v[162:165], v149 offset:2048
	ds_read_b128 v[166:169], v151
	s_waitcnt lgkmcnt(0)
	v_mfma_f32_32x32x16_bf16 v[112:127], v[158:161], v[166:169], v[112:127]
	s_mov_b32 m0, s9
	v_mfma_f32_32x32x16_bf16 v[48:63], v[162:165], v[166:169], v[48:63]
	ds_read_b128 v[166:169], v151 offset:2048
	s_waitcnt lgkmcnt(0)
	v_mfma_f32_32x32x16_bf16 v[96:111], v[158:161], v[166:169], v[96:111]
	v_mfma_f32_32x32x16_bf16 v[32:47], v[162:165], v[166:169], v[32:47]
	ds_read_b128 v[166:169], v151 offset:4096
	s_waitcnt lgkmcnt(0)
	v_mfma_f32_32x32x16_bf16 v[80:95], v[158:161], v[166:169], v[80:95]
	v_mfma_f32_32x32x16_bf16 v[16:31], v[162:165], v[166:169], v[16:31]
	ds_read_b128 v[166:169], v151 offset:6144
	s_waitcnt lgkmcnt(0)
	v_mfma_f32_32x32x16_bf16 v[64:79], v[158:161], v[166:169], v[64:79]
	v_mfma_f32_32x32x16_bf16 v[0:15], v[162:165], v[166:169], v[0:15]
	ds_read_b128 v[158:161], v155
	ds_read_b128 v[162:165], v155 offset:2048
	ds_read_b128 v[166:169], v156
	s_waitcnt lgkmcnt(0)
	v_mfma_f32_32x32x16_bf16 v[112:127], v[158:161], v[166:169], v[112:127]
	v_mfma_f32_32x32x16_bf16 v[48:63], v[162:165], v[166:169], v[48:63]
	ds_read_b128 v[166:169], v156 offset:2048
	s_waitcnt lgkmcnt(0)
	v_mfma_f32_32x32x16_bf16 v[96:111], v[158:161], v[166:169], v[96:111]
	v_mfma_f32_32x32x16_bf16 v[32:47], v[162:165], v[166:169], v[32:47]
	ds_read_b128 v[166:169], v156 offset:4096
	s_waitcnt lgkmcnt(0)
	v_mfma_f32_32x32x16_bf16 v[80:95], v[158:161], v[166:169], v[80:95]
	v_mfma_f32_32x32x16_bf16 v[16:31], v[162:165], v[166:169], v[16:31]
	ds_read_b128 v[166:169], v156 offset:6144
	s_waitcnt vmcnt(8)
	s_waitcnt lgkmcnt(0)
	s_barrier
; #define MFMA(a, b, c) __builtin_amdgcn_mfma_f32_32x32x16_bf16((a), (b), (c), 0, 0, 0)
; #define WAIT_V(n) asm volatile("s_waitcnt vmcnt(%0)" ::"n"(n) : "memory")
; #define RAW_BARRIER() do { asm volatile("s_waitcnt lgkmcnt(0)" ::: "memory"); __builtin_amdgcn_s_barrier(); } while (0)
; template <typename FA, typename FB, typename FE>
; DI void gemm_tile(char* lds, int K, int astride, int bstride, FA arow, FB brow, FE epi) {
;     ...
;   for (int kt = 0; kt < nk; ++kt) {
;     if (kt + 2 < nk) WAIT_V(8); else if (kt + 1 < nk) WAIT_V(4); else WAIT_V(0);
;     RAW_BARRIER();
;     if (kt + 3 < nk) stage((kt + 3) & 3, kt + 3);
;     const char* sa = lds + (kt & 3) * 32768 + wm * 4096;
;     const char* sb = lds + (kt & 3) * 32768 + 16384 + wn * 8192;
; #pragma unroll
;     for (int ks = 0; ks < 2; ++ks) {
;       bf16x8 a0 = *(const bf16x8*)(sa + foff[ks]), a1 = *(const bf16x8*)(sa + 2048 + foff[ks]);
; #pragma unroll
;       for (int nt = 0; nt < 4; ++nt) {
;         bf16x8 bb = *(const bf16x8*)(sb + nt * 2048 + foff[ks]);
;         acc[0][nt] = MFMA(a0, bb, acc[0][nt]);
;         acc[1][nt] = MFMA(a1, bb, acc[1][nt]);
;       }
;     }
	s_waitcnt lgkmcnt(0)
	v_mfma_f32_32x32x16_bf16 v[64:79], v[158:161], v[166:169], v[64:79]
	v_lshl_add_u64 v[158:159], v[136:137], 0, s[86:87]
	global_load_lds_dwordx4 v[158:159], off
	v_lshl_add_u64 v[158:159], v[138:139], 0, s[88:89]
	s_mov_b32 m0, s10
	s_nop 0
	global_load_lds_dwordx4 v[158:159], off
	v_lshl_add_u64 v[158:159], v[140:141], 0, s[86:87]
	s_mov_b32 m0, s11
	v_mfma_f32_32x32x16_bf16 v[0:15], v[162:165], v[166:169], v[0:15]
	global_load_lds_dwordx4 v[158:159], off
	v_lshl_add_u64 v[158:159], v[142:143], 0, s[88:89]
	s_mov_b32 m0, s12
	s_nop 0
	global_load_lds_dwordx4 v[158:159], off
	ds_read_b128 v[158:161], v146
	ds_read_b128 v[162:165], v146 offset:2048
	ds_read_b128 v[166:169], v150
	s_waitcnt lgkmcnt(0)
	v_mfma_f32_32x32x16_bf16 v[112:127], v[158:161], v[166:169], v[112:127]
	s_mov_b32 m0, s5
	v_mfma_f32_32x32x16_bf16 v[48:63], v[162:165], v[166:169], v[48:63]
	ds_read_b128 v[166:169], v150 offset:2048
	s_waitcnt lgkmcnt(0)
	v_mfma_f32_32x32x16_bf16 v[96:111], v[158:161], v[166:169], v[96:111]
	v_mfma_f32_32x32x16_bf16 v[32:47], v[162:165], v[166:169], v[32:47]
	ds_read_b128 v[166:169], v150 offset:4096
	s_waitcnt lgkmcnt(0)
	v_mfma_f32_32x32x16_bf16 v[80:95], v[158:161], v[166:169], v[80:95]
	v_mfma_f32_32x32x16_bf16 v[16:31], v[162:165], v[166:169], v[16:31]
	ds_read_b128 v[166:169], v150 offset:6144
	s_waitcnt lgkmcnt(0)
	v_mfma_f32_32x32x16_bf16 v[64:79], v[158:161], v[166:169], v[64:79]
	v_mfma_f32_32x32x16_bf16 v[0:15], v[162:165], v[166:169], v[0:15]
	ds_read_b128 v[158:161], v152
	ds_read_b128 v[162:165], v152 offset:2048
	ds_read_b128 v[166:169], v154
	s_waitcnt lgkmcnt(0)
	v_mfma_f32_32x32x16_bf16 v[112:127], v[158:161], v[166:169], v[112:127]
	v_mfma_f32_32x32x16_bf16 v[48:63], v[162:165], v[166:169], v[48:63]
	ds_read_b128 v[166:169], v154 offset:2048
	s_waitcnt lgkmcnt(0)
	v_mfma_f32_32x32x16_bf16 v[96:111], v[158:161], v[166:169], v[96:111]
	v_mfma_f32_32x32x16_bf16 v[32:47], v[162:165], v[166:169], v[32:47]
	ds_read_b128 v[166:169], v154 offset:4096
	s_waitcnt lgkmcnt(0)
	v_mfma_f32_32x32x16_bf16 v[80:95], v[158:161], v[166:169], v[80:95]
	v_mfma_f32_32x32x16_bf16 v[16:31], v[162:165], v[166:169], v[16:31]
	ds_read_b128 v[166:169], v154 offset:6144
	s_waitcnt vmcnt(8)
	s_waitcnt lgkmcnt(0)
	s_barrier
	s_waitcnt lgkmcnt(0)
	v_mfma_f32_32x32x16_bf16 v[64:79], v[158:161], v[166:169], v[64:79]
	v_lshl_add_u64 v[158:159], v[136:137], 0, s[90:91]
	global_load_lds_dwordx4 v[158:159], off
	v_lshl_add_u64 v[158:159], v[138:139], 0, s[92:93]
	s_mov_b32 m0, s6
	s_nop 0
	global_load_lds_dwordx4 v[158:159], off
	v_lshl_add_u64 v[158:159], v[140:141], 0, s[90:91]
	s_mov_b32 m0, s7
	v_mfma_f32_32x32x16_bf16 v[0:15], v[162:165], v[166:169], v[0:15]
	global_load_lds_dwordx4 v[158:159], off
	v_lshl_add_u64 v[158:159], v[142:143], 0, s[92:93]
	s_mov_b32 m0, s8
	s_nop 0
	global_load_lds_dwordx4 v[158:159], off
	ds_read_b128 v[158:161], v128
	ds_read_b128 v[162:165], v128 offset:2048
	ds_read_b128 v[166:169], v144 offset:16384
	s_waitcnt lgkmcnt(0)
	v_mfma_f32_32x32x16_bf16 v[112:127], v[158:161], v[166:169], v[112:127]
	s_mov_b32 m0, s17
	v_mfma_f32_32x32x16_bf16 v[48:63], v[162:165], v[166:169], v[48:63]
	ds_read_b128 v[166:169], v144 offset:18432
	s_waitcnt lgkmcnt(0)
	v_mfma_f32_32x32x16_bf16 v[96:111], v[158:161], v[166:169], v[96:111]
	v_mfma_f32_32x32x16_bf16 v[32:47], v[162:165], v[166:169], v[32:47]
	ds_read_b128 v[166:169], v144 offset:20480
	s_waitcnt lgkmcnt(0)
	v_mfma_f32_32x32x16_bf16 v[80:95], v[158:161], v[166:169], v[80:95]
	v_mfma_f32_32x32x16_bf16 v[16:31], v[162:165], v[166:169], v[16:31]
	ds_read_b128 v[166:169], v144 offset:22528
	s_waitcnt lgkmcnt(0)
	v_mfma_f32_32x32x16_bf16 v[64:79], v[158:161], v[166:169], v[64:79]
	v_mfma_f32_32x32x16_bf16 v[0:15], v[162:165], v[166:169], v[0:15]
	ds_read_b128 v[158:161], v147
	ds_read_b128 v[162:165], v147 offset:2048
	ds_read_b128 v[166:169], v148 offset:16384
	s_waitcnt lgkmcnt(0)
	v_mfma_f32_32x32x16_bf16 v[112:127], v[158:161], v[166:169], v[112:127]
	v_mfma_f32_32x32x16_bf16 v[48:63], v[162:165], v[166:169], v[48:63]
	ds_read_b128 v[166:169], v148 offset:18432
	s_waitcnt lgkmcnt(0)
	v_mfma_f32_32x32x16_bf16 v[96:111], v[158:161], v[166:169], v[96:111]
	v_mfma_f32_32x32x16_bf16 v[32:47], v[162:165], v[166:169], v[32:47]
	ds_read_b128 v[166:169], v148 offset:20480
	s_waitcnt lgkmcnt(0)
	v_mfma_f32_32x32x16_bf16 v[80:95], v[158:161], v[166:169], v[80:95]
	v_mfma_f32_32x32x16_bf16 v[16:31], v[162:165], v[166:169], v[16:31]
	ds_read_b128 v[166:169], v148 offset:22528
	s_waitcnt vmcnt(8)
	s_waitcnt lgkmcnt(0)
	s_barrier
; #define MFMA(a, b, c) __builtin_amdgcn_mfma_f32_32x32x16_bf16((a), (b), (c), 0, 0, 0)
; #define WAIT_V(n) asm volatile("s_waitcnt vmcnt(%0)" ::"n"(n) : "memory")
; #define RAW_BARRIER() do { asm volatile("s_waitcnt lgkmcnt(0)" ::: "memory"); __builtin_amdgcn_s_barrier(); } while (0)
; template <typename FA, typename FB, typename FE>
; DI void gemm_tile(char* lds, int K, int astride, int bstride, FA arow, FB brow, FE epi) {
;     ...
;   for (int kt = 0; kt < nk; ++kt) {
;     if (kt + 2 < nk) WAIT_V(8); else if (kt + 1 < nk) WAIT_V(4); else WAIT_V(0);
;     RAW_BARRIER();
;     if (kt + 3 < nk) stage((kt + 3) & 3, kt + 3);
;     const char* sa = lds + (kt & 3) * 32768 + wm * 4096;
;     const char* sb = lds + (kt & 3) * 32768 + 16384 + wn * 8192;
; #pragma unroll
;     for (int ks = 0; ks < 2; ++ks) {
;       bf16x8 a0 = *(const bf16x8*)(sa + foff[ks]), a1 = *(const bf16x8*)(sa + 2048 + foff[ks]);
; #pragma unroll
;       for (int nt = 0; nt < 4; ++nt) {
;         bf16x8 bb = *(const bf16x8*)(sb + nt * 2048 + foff[ks]);
;         acc[0][nt] = MFMA(a0, bb, acc[0][nt]);
;         acc[1][nt] = MFMA(a1, bb, acc[1][nt]);
;       }
;     }
	s_waitcnt lgkmcnt(0)
	v_mfma_f32_32x32x16_bf16 v[64:79], v[158:161], v[166:169], v[64:79]
	v_lshl_add_u64 v[158:159], v[136:137], 0, s[94:95]
	global_load_lds_dwordx4 v[158:159], off
	v_lshl_add_u64 v[158:159], v[138:139], 0, s[96:97]
	s_mov_b32 m0, s18
	s_nop 0
	global_load_lds_dwordx4 v[158:159], off
	v_lshl_add_u64 v[158:159], v[140:141], 0, s[94:95]
	s_mov_b32 m0, s19
	v_mfma_f32_32x32x16_bf16 v[0:15], v[162:165], v[166:169], v[0:15]
	global_load_lds_dwordx4 v[158:159], off
	v_lshl_add_u64 v[158:159], v[142:143], 0, s[96:97]
	s_mov_b32 m0, s20
	s_nop 0
	global_load_lds_dwordx4 v[158:159], off
	ds_read_b128 v[158:161], v128 offset:32768
	ds_read_b128 v[162:165], v128 offset:34816
	ds_read_b128 v[166:169], v144 offset:49152
	s_waitcnt lgkmcnt(0)
	v_mfma_f32_32x32x16_bf16 v[112:127], v[158:161], v[166:169], v[112:127]
	s_mov_b32 m0, s13
	v_mfma_f32_32x32x16_bf16 v[48:63], v[162:165], v[166:169], v[48:63]
	ds_read_b128 v[166:169], v144 offset:51200
	s_waitcnt lgkmcnt(0)
	v_mfma_f32_32x32x16_bf16 v[96:111], v[158:161], v[166:169], v[96:111]
	v_mfma_f32_32x32x16_bf16 v[32:47], v[162:165], v[166:169], v[32:47]
	ds_read_b128 v[166:169], v144 offset:53248
	s_waitcnt lgkmcnt(0)
	v_mfma_f32_32x32x16_bf16 v[80:95], v[158:161], v[166:169], v[80:95]
	v_mfma_f32_32x32x16_bf16 v[16:31], v[162:165], v[166:169], v[16:31]
	ds_read_b128 v[166:169], v144 offset:55296
	s_waitcnt lgkmcnt(0)
	v_mfma_f32_32x32x16_bf16 v[64:79], v[158:161], v[166:169], v[64:79]
	v_mfma_f32_32x32x16_bf16 v[0:15], v[162:165], v[166:169], v[0:15]
	ds_read_b128 v[158:161], v147 offset:32768
	ds_read_b128 v[162:165], v147 offset:34816
	ds_read_b128 v[166:169], v148 offset:49152
	s_waitcnt lgkmcnt(0)
	v_mfma_f32_32x32x16_bf16 v[112:127], v[158:161], v[166:169], v[112:127]
	v_mfma_f32_32x32x16_bf16 v[48:63], v[162:165], v[166:169], v[48:63]
	ds_read_b128 v[166:169], v148 offset:51200
	s_waitcnt lgkmcnt(0)
	v_mfma_f32_32x32x16_bf16 v[96:111], v[158:161], v[166:169], v[96:111]
	v_mfma_f32_32x32x16_bf16 v[32:47], v[162:165], v[166:169], v[32:47]
	ds_read_b128 v[166:169], v148 offset:53248
	s_waitcnt lgkmcnt(0)
	v_mfma_f32_32x32x16_bf16 v[80:95], v[158:161], v[166:169], v[80:95]
	v_mfma_f32_32x32x16_bf16 v[16:31], v[162:165], v[166:169], v[16:31]
	ds_read_b128 v[166:169], v148 offset:55296
	s_waitcnt vmcnt(8)
	s_waitcnt lgkmcnt(0)
	s_barrier
	s_waitcnt lgkmcnt(0)
	v_mfma_f32_32x32x16_bf16 v[64:79], v[158:161], v[166:169], v[64:79]
	v_lshl_add_u64 v[158:159], v[136:137], 0, s[52:53]
	global_load_lds_dwordx4 v[158:159], off
	v_lshl_add_u64 v[158:159], v[138:139], 0, s[54:55]
	s_mov_b32 m0, s14
	s_nop 0
	global_load_lds_dwordx4 v[158:159], off
	v_lshl_add_u64 v[158:159], v[140:141], 0, s[52:53]
	s_mov_b32 m0, s15
	v_mfma_f32_32x32x16_bf16 v[0:15], v[162:165], v[166:169], v[0:15]
	global_load_lds_dwordx4 v[158:159], off
	v_lshl_add_u64 v[158:159], v[142:143], 0, s[54:55]
	s_mov_b32 m0, s16
	s_nop 0
	global_load_lds_dwordx4 v[158:159], off
	ds_read_b128 v[158:161], v149
	ds_read_b128 v[162:165], v149 offset:2048
	ds_read_b128 v[166:169], v151
	s_waitcnt lgkmcnt(0)
	v_mfma_f32_32x32x16_bf16 v[112:127], v[158:161], v[166:169], v[112:127]
	s_mov_b32 m0, s9
	v_mfma_f32_32x32x16_bf16 v[48:63], v[162:165], v[166:169], v[48:63]
	ds_read_b128 v[166:169], v151 offset:2048
	s_waitcnt lgkmcnt(0)
	v_mfma_f32_32x32x16_bf16 v[96:111], v[158:161], v[166:169], v[96:111]
	v_mfma_f32_32x32x16_bf16 v[32:47], v[162:165], v[166:169], v[32:47]
	ds_read_b128 v[166:169], v151 offset:4096
	s_waitcnt lgkmcnt(0)
	v_mfma_f32_32x32x16_bf16 v[80:95], v[158:161], v[166:169], v[80:95]
	v_mfma_f32_32x32x16_bf16 v[16:31], v[162:165], v[166:169], v[16:31]
	ds_read_b128 v[166:169], v151 offset:6144
	s_waitcnt lgkmcnt(0)
	v_mfma_f32_32x32x16_bf16 v[64:79], v[158:161], v[166:169], v[64:79]
	v_mfma_f32_32x32x16_bf16 v[0:15], v[162:165], v[166:169], v[0:15]
	ds_read_b128 v[158:161], v155
	ds_read_b128 v[162:165], v155 offset:2048
	ds_read_b128 v[166:169], v156
	s_waitcnt lgkmcnt(0)
	v_mfma_f32_32x32x16_bf16 v[112:127], v[158:161], v[166:169], v[112:127]
	v_mfma_f32_32x32x16_bf16 v[48:63], v[162:165], v[166:169], v[48:63]
	ds_read_b128 v[166:169], v156 offset:2048
	s_waitcnt lgkmcnt(0)
	v_mfma_f32_32x32x16_bf16 v[96:111], v[158:161], v[166:169], v[96:111]
	v_mfma_f32_32x32x16_bf16 v[32:47], v[162:165], v[166:169], v[32:47]
	ds_read_b128 v[166:169], v156 offset:4096
	s_waitcnt lgkmcnt(0)
	v_mfma_f32_32x32x16_bf16 v[80:95], v[158:161], v[166:169], v[80:95]
	v_mfma_f32_32x32x16_bf16 v[16:31], v[162:165], v[166:169], v[16:31]
	ds_read_b128 v[166:169], v156 offset:6144
	s_waitcnt vmcnt(8)
	s_waitcnt lgkmcnt(0)
	s_barrier
; #define MFMA(a, b, c) __builtin_amdgcn_mfma_f32_32x32x16_bf16((a), (b), (c), 0, 0, 0)
; #define WAIT_V(n) asm volatile("s_waitcnt vmcnt(%0)" ::"n"(n) : "memory")
; #define RAW_BARRIER() do { asm volatile("s_waitcnt lgkmcnt(0)" ::: "memory"); __builtin_amdgcn_s_barrier(); } while (0)
; template <typename FA, typename FB, typename FE>
; DI void gemm_tile(char* lds, int K, int astride, int bstride, FA arow, FB brow, FE epi) {
;     ...
;   for (int kt = 0; kt < nk; ++kt) {
;     if (kt + 2 < nk) WAIT_V(8); else if (kt + 1 < nk) WAIT_V(4); else WAIT_V(0);
;     RAW_BARRIER();
;     if (kt + 3 < nk) stage((kt + 3) & 3, kt + 3);
;     const char* sa = lds + (kt & 3) * 32768 + wm * 4096;
;     const char* sb = lds + (kt & 3) * 32768 + 16384 + wn * 8192;
; #pragma unroll
;     for (int ks = 0; ks < 2; ++ks) {
;       bf16x8 a0 = *(const bf16x8*)(sa + foff[ks]), a1 = *(const bf16x8*)(sa + 2048 + foff[ks]);
; #pragma unroll
;       for (int nt = 0; nt < 4; ++nt) {
;         bf16x8 bb = *(const bf16x8*)(sb + nt * 2048 + foff[ks]);
;         acc[0][nt] = MFMA(a0, bb, acc[0][nt]);
;         acc[1][nt] = MFMA(a1, bb, acc[1][nt]);
;       }
;     }
	s_waitcnt lgkmcnt(0)
	v_mfma_f32_32x32x16_bf16 v[64:79], v[158:161], v[166:169], v[64:79]
	v_lshl_add_u64 v[158:159], v[136:137], 0, s[56:57]
	global_load_lds_dwordx4 v[158:159], off
	v_lshl_add_u64 v[158:159], v[138:139], 0, s[58:59]
	s_mov_b32 m0, s10
	v_lshl_add_u64 v[136:137], v[136:137], 0, s[60:61]
	global_load_lds_dwordx4 v[158:159], off
	v_lshl_add_u64 v[158:159], v[140:141], 0, s[56:57]
	s_mov_b32 m0, s11
	v_mfma_f32_32x32x16_bf16 v[0:15], v[162:165], v[166:169], v[0:15]
	global_load_lds_dwordx4 v[158:159], off
	v_lshl_add_u64 v[158:159], v[142:143], 0, s[58:59]
	s_mov_b32 m0, s12
	s_nop 0
	global_load_lds_dwordx4 v[158:159], off
	ds_read_b128 v[158:161], v146
	ds_read_b128 v[162:165], v146 offset:2048
	ds_read_b128 v[166:169], v150
	s_waitcnt lgkmcnt(0)
	v_mfma_f32_32x32x16_bf16 v[112:127], v[158:161], v[166:169], v[112:127]
	s_mov_b32 m0, s5
	v_mfma_f32_32x32x16_bf16 v[48:63], v[162:165], v[166:169], v[48:63]
	ds_read_b128 v[166:169], v150 offset:2048
	s_waitcnt lgkmcnt(0)
	v_mfma_f32_32x32x16_bf16 v[96:111], v[158:161], v[166:169], v[96:111]
	v_mfma_f32_32x32x16_bf16 v[32:47], v[162:165], v[166:169], v[32:47]
	ds_read_b128 v[166:169], v150 offset:4096
	s_waitcnt lgkmcnt(0)
	v_mfma_f32_32x32x16_bf16 v[80:95], v[158:161], v[166:169], v[80:95]
	v_mfma_f32_32x32x16_bf16 v[16:31], v[162:165], v[166:169], v[16:31]
	ds_read_b128 v[166:169], v150 offset:6144
	s_waitcnt lgkmcnt(0)
	v_mfma_f32_32x32x16_bf16 v[64:79], v[158:161], v[166:169], v[64:79]
	v_mfma_f32_32x32x16_bf16 v[0:15], v[162:165], v[166:169], v[0:15]
	ds_read_b128 v[158:161], v152
	ds_read_b128 v[162:165], v152 offset:2048
	ds_read_b128 v[166:169], v154
	s_waitcnt lgkmcnt(0)
	v_mfma_f32_32x32x16_bf16 v[112:127], v[158:161], v[166:169], v[112:127]
	v_mfma_f32_32x32x16_bf16 v[48:63], v[162:165], v[166:169], v[48:63]
	ds_read_b128 v[166:169], v154 offset:2048
	s_waitcnt lgkmcnt(0)
	v_mfma_f32_32x32x16_bf16 v[96:111], v[158:161], v[166:169], v[96:111]
	v_mfma_f32_32x32x16_bf16 v[32:47], v[162:165], v[166:169], v[32:47]
	ds_read_b128 v[166:169], v154 offset:4096
	s_waitcnt lgkmcnt(0)
	v_mfma_f32_32x32x16_bf16 v[80:95], v[158:161], v[166:169], v[80:95]
	v_mfma_f32_32x32x16_bf16 v[16:31], v[162:165], v[166:169], v[16:31]
	ds_read_b128 v[166:169], v154 offset:6144
	s_waitcnt vmcnt(8)
	s_waitcnt lgkmcnt(0)
	s_barrier
	global_load_lds_dwordx4 v[136:137], off
	v_lshl_add_u64 v[136:137], v[138:139], 0, s[62:63]
	s_mov_b32 m0, s6
	s_waitcnt lgkmcnt(0)
	v_mfma_f32_32x32x16_bf16 v[64:79], v[158:161], v[166:169], v[64:79]
	global_load_lds_dwordx4 v[136:137], off
	v_lshl_add_u64 v[136:137], v[140:141], 0, s[60:61]
	s_mov_b32 m0, s7
	s_nop 0
	global_load_lds_dwordx4 v[136:137], off
	v_lshl_add_u64 v[136:137], v[142:143], 0, s[62:63]
	s_mov_b32 m0, s8
	v_mfma_f32_32x32x16_bf16 v[0:15], v[162:165], v[166:169], v[0:15]
	global_load_lds_dwordx4 v[136:137], off
	ds_read_b128 v[136:139], v128
	ds_read_b128 v[140:143], v128 offset:2048
	ds_read_b128 v[158:161], v144 offset:16384
	s_waitcnt lgkmcnt(0)
	v_mfma_f32_32x32x16_bf16 v[112:127], v[136:139], v[158:161], v[112:127]
	v_mfma_f32_32x32x16_bf16 v[48:63], v[140:143], v[158:161], v[48:63]
	ds_read_b128 v[158:161], v144 offset:18432
	s_waitcnt lgkmcnt(0)
	v_mfma_f32_32x32x16_bf16 v[96:111], v[136:139], v[158:161], v[96:111]
	v_mfma_f32_32x32x16_bf16 v[32:47], v[140:143], v[158:161], v[32:47]
	ds_read_b128 v[158:161], v144 offset:20480
	s_waitcnt lgkmcnt(0)
	v_mfma_f32_32x32x16_bf16 v[80:95], v[136:139], v[158:161], v[80:95]
	v_mfma_f32_32x32x16_bf16 v[16:31], v[140:143], v[158:161], v[16:31]
	ds_read_b128 v[158:161], v144 offset:22528
	s_waitcnt lgkmcnt(0)
	v_mfma_f32_32x32x16_bf16 v[64:79], v[136:139], v[158:161], v[64:79]
	v_mfma_f32_32x32x16_bf16 v[0:15], v[140:143], v[158:161], v[0:15]
	ds_read_b128 v[136:139], v147
	ds_read_b128 v[140:143], v147 offset:2048
	ds_read_b128 v[158:161], v148 offset:16384
	s_waitcnt lgkmcnt(0)
	v_mfma_f32_32x32x16_bf16 v[112:127], v[136:139], v[158:161], v[112:127]
	v_mfma_f32_32x32x16_bf16 v[48:63], v[140:143], v[158:161], v[48:63]
	ds_read_b128 v[158:161], v148 offset:18432
	s_waitcnt lgkmcnt(0)
	v_mfma_f32_32x32x16_bf16 v[96:111], v[136:139], v[158:161], v[96:111]
	v_mfma_f32_32x32x16_bf16 v[32:47], v[140:143], v[158:161], v[32:47]
	ds_read_b128 v[158:161], v148 offset:20480
	s_waitcnt lgkmcnt(0)
	v_mfma_f32_32x32x16_bf16 v[80:95], v[136:139], v[158:161], v[80:95]
	v_mfma_f32_32x32x16_bf16 v[16:31], v[140:143], v[158:161], v[16:31]
	ds_read_b128 v[158:161], v148 offset:22528
	s_waitcnt vmcnt(8)
	s_waitcnt lgkmcnt(0)
	s_barrier
	s_waitcnt lgkmcnt(0)
	v_mfma_f32_32x32x16_bf16 v[64:79], v[136:139], v[158:161], v[64:79]
	v_mfma_f32_32x32x16_bf16 v[0:15], v[140:143], v[158:161], v[0:15]
	ds_read_b128 v[136:139], v148 offset:55296
	ds_read_b128 v[140:143], v148 offset:53248
	ds_read_b128 v[158:161], v148 offset:51200
	ds_read_b128 v[162:165], v148 offset:49152
	ds_read_b128 v[166:169], v147 offset:34816
	ds_read_b128 v[170:173], v147 offset:32768
	ds_read_b128 v[174:177], v144 offset:55296
	ds_read_b128 v[178:181], v144 offset:53248
	ds_read_b128 v[182:185], v144 offset:51200
	ds_read_b128 v[220:223], v144 offset:49152
	ds_read_b128 v[224:227], v128 offset:34816
	ds_read_b128 v[228:231], v128 offset:32768
	s_waitcnt vmcnt(4)
	s_waitcnt lgkmcnt(0)
	s_barrier
; #define MFMA(a, b, c) __builtin_amdgcn_mfma_f32_32x32x16_bf16((a), (b), (c), 0, 0, 0)
; DI unsigned pk2(float a, float b) { fl2_t f = {a, b}; bf2_t r = __builtin_convertvector(f, bf2_t); return __builtin_bit_cast(unsigned, r); }
; #define RAW_BARRIER() do { asm volatile("s_waitcnt lgkmcnt(0)" ::: "memory"); __builtin_amdgcn_s_barrier(); } while (0)
; template <typename FA, typename FB, typename FE>
; DI void gemm_tile(char* lds, int K, int astride, int bstride, FA arow, FB brow, FE epi) {
;     ...
; #pragma unroll
;     for (int ks = 0; ks < 2; ++ks) {
;       bf16x8 a0 = *(const bf16x8*)(sa + foff[ks]), a1 = *(const bf16x8*)(sa + 2048 + foff[ks]);
; #pragma unroll
;       for (int nt = 0; nt < 4; ++nt) {
;         bf16x8 bb = *(const bf16x8*)(sb + nt * 2048 + foff[ks]);
;         acc[0][nt] = MFMA(a0, bb, acc[0][nt]);
;         acc[1][nt] = MFMA(a1, bb, acc[1][nt]);
;       }
;     }
;   }
;   RAW_BARRIER();
;   bfr* Cs = (bfr*)lds;
; #pragma unroll
;   for (int mt = 0; mt < 2; ++mt)
; #pragma unroll
;     for (int nt = 0; nt < 4; ++nt)
; #pragma unroll
;       for (int i = 0; i < 16; i += 2) {
;         const int row = wm * 64 + mt * 32 + (i & 3) + 8 * (i >> 2) + 4 * h8;
;         const unsigned pr = pk2(acc[mt][nt][i], acc[mt][nt][i + 1]);
;         Cs[row * CSS + wn * 128 + nt * 32 + r] = (bfr)(pr & 0xffffu);
;         Cs[(row + 1) * CSS + wn * 128 + nt * 32 + r] = (bfr)(pr >> 16);
;       }
	v_lshl_or_b32 v128, s1, 6, v191
	s_movk_i32 s1, 0x210
	s_waitcnt lgkmcnt(0)
	v_mfma_f32_32x32x16_bf16 v[112:127], v[228:231], v[220:223], v[112:127]
	v_mfma_f32_32x32x16_bf16 v[48:63], v[224:227], v[220:223], v[48:63]
	v_mfma_f32_32x32x16_bf16 v[96:111], v[228:231], v[182:185], v[96:111]
	v_mfma_f32_32x32x16_bf16 v[32:47], v[224:227], v[182:185], v[32:47]
	v_mfma_f32_32x32x16_bf16 v[80:95], v[228:231], v[178:181], v[80:95]
	v_mfma_f32_32x32x16_bf16 v[16:31], v[224:227], v[178:181], v[16:31]
	v_mfma_f32_32x32x16_bf16 v[64:79], v[228:231], v[174:177], v[64:79]
	v_mfma_f32_32x32x16_bf16 v[0:15], v[224:227], v[174:177], v[0:15]
	v_mfma_f32_32x32x16_bf16 v[112:127], v[170:173], v[162:165], v[112:127]
	v_mfma_f32_32x32x16_bf16 v[48:63], v[166:169], v[162:165], v[48:63]
	v_mfma_f32_32x32x16_bf16 v[96:111], v[170:173], v[158:161], v[96:111]
	v_mfma_f32_32x32x16_bf16 v[32:47], v[166:169], v[158:161], v[32:47]
	v_mfma_f32_32x32x16_bf16 v[80:95], v[170:173], v[140:143], v[80:95]
	v_mfma_f32_32x32x16_bf16 v[16:31], v[166:169], v[140:143], v[16:31]
	v_mfma_f32_32x32x16_bf16 v[64:79], v[170:173], v[136:139], v[64:79]
	v_mfma_f32_32x32x16_bf16 v[0:15], v[166:169], v[136:139], v[0:15]
	ds_read_b128 v[136:139], v156 offset:6144
	ds_read_b128 v[140:143], v156 offset:4096
	ds_read_b128 v[158:161], v156 offset:2048
	ds_read_b128 v[162:165], v156
	ds_read_b128 v[166:169], v155 offset:2048
	ds_read_b128 v[170:173], v155
	ds_read_b128 v[174:177], v151 offset:6144
	ds_read_b128 v[178:181], v151 offset:4096
	ds_read_b128 v[182:185], v151 offset:2048
	ds_read_b128 v[220:223], v151
	ds_read_b128 v[224:227], v149 offset:2048
	ds_read_b128 v[228:231], v149
	s_waitcnt vmcnt(0)
	s_waitcnt lgkmcnt(0)
	s_barrier
	s_waitcnt lgkmcnt(0)
	v_mfma_f32_32x32x16_bf16 v[112:127], v[228:231], v[220:223], v[112:127]
	v_mfma_f32_32x32x16_bf16 v[48:63], v[224:227], v[220:223], v[48:63]
	v_mfma_f32_32x32x16_bf16 v[96:111], v[228:231], v[182:185], v[96:111]
	v_mfma_f32_32x32x16_bf16 v[32:47], v[224:227], v[182:185], v[32:47]
	v_mfma_f32_32x32x16_bf16 v[80:95], v[228:231], v[178:181], v[80:95]
	v_mfma_f32_32x32x16_bf16 v[16:31], v[224:227], v[178:181], v[16:31]
	v_mfma_f32_32x32x16_bf16 v[64:79], v[228:231], v[174:177], v[64:79]
	v_mfma_f32_32x32x16_bf16 v[0:15], v[224:227], v[174:177], v[0:15]
	v_mfma_f32_32x32x16_bf16 v[112:127], v[170:173], v[162:165], v[112:127]
	v_mfma_f32_32x32x16_bf16 v[48:63], v[166:169], v[162:165], v[48:63]
	v_mfma_f32_32x32x16_bf16 v[96:111], v[170:173], v[158:161], v[96:111]
	v_mfma_f32_32x32x16_bf16 v[32:47], v[166:169], v[158:161], v[32:47]
	v_mfma_f32_32x32x16_bf16 v[80:95], v[170:173], v[140:143], v[80:95]
	v_mfma_f32_32x32x16_bf16 v[16:31], v[166:169], v[140:143], v[16:31]
	v_mfma_f32_32x32x16_bf16 v[64:79], v[170:173], v[136:139], v[64:79]
	v_mfma_f32_32x32x16_bf16 v[0:15], v[166:169], v[136:139], v[0:15]
	ds_read_b128 v[136:139], v154 offset:6144
	ds_read_b128 v[140:143], v154 offset:4096
	ds_read_b128 v[156:159], v154 offset:2048
	ds_read_b128 v[160:163], v154
	ds_read_b128 v[164:167], v152 offset:2048
	ds_read_b128 v[168:171], v152
	ds_read_b128 v[172:175], v150 offset:6144
	ds_read_b128 v[176:179], v150 offset:4096
	ds_read_b128 v[180:183], v150 offset:2048
	ds_read_b128 v[148:151], v150
	ds_read_b128 v[220:223], v146 offset:2048
	ds_read_b128 v[224:227], v146
	s_waitcnt lgkmcnt(0)
	s_barrier
	s_waitcnt lgkmcnt(0)
	v_mfma_f32_32x32x16_bf16 v[112:127], v[224:227], v[148:151], v[112:127]
	v_mfma_f32_32x32x16_bf16 v[96:111], v[224:227], v[180:183], v[96:111]
	v_mfma_f32_32x32x16_bf16 v[64:79], v[224:227], v[172:175], v[64:79]
	v_mfma_f32_32x32x16_bf16 v[0:15], v[220:223], v[172:175], v[0:15]
	v_mfma_f32_32x32x16_bf16 v[112:127], v[168:171], v[160:163], v[112:127]
	v_mfma_f32_32x32x16_bf16 v[80:95], v[224:227], v[176:179], v[80:95]
	v_mfma_f32_32x32x16_bf16 v[96:111], v[168:171], v[156:159], v[96:111]
	v_mfma_f32_32x32x16_bf16 v[64:79], v[168:171], v[136:139], v[64:79]
	s_nop 10
	v_cvt_pk_bf16_f32 v96, v96, v97
	v_mfma_f32_32x32x16_bf16 v[0:15], v[164:167], v[136:139], v[0:15]
	v_cvt_pk_bf16_f32 v136, v112, v113
	v_lshl_or_b32 v112, s4, 8, v216
	v_mad_u64_u32 v[112:113], s[4:5], v128, s1, v[112:113]
	v_cvt_pk_bf16_f32 v113, v114, v115
	ds_write_b16 v112, v136
	ds_write_b16_d16_hi v112, v136 offset:528
	ds_write_b16 v112, v113 offset:1056
	ds_write_b16_d16_hi v112, v113 offset:1584
	v_cvt_pk_bf16_f32 v113, v116, v117
	ds_write_b16 v112, v113 offset:4224
	ds_write_b16_d16_hi v112, v113 offset:4752
	v_cvt_pk_bf16_f32 v113, v118, v119
	ds_write_b16 v112, v113 offset:5280
	ds_write_b16_d16_hi v112, v113 offset:5808
	v_cvt_pk_bf16_f32 v113, v120, v121
	ds_write_b16 v112, v113 offset:8448
	ds_write_b16_d16_hi v112, v113 offset:8976
	v_cvt_pk_bf16_f32 v113, v122, v123
	v_mfma_f32_32x32x16_bf16 v[80:95], v[168:171], v[140:143], v[80:95]
	ds_write_b16 v112, v113 offset:9504
	ds_write_b16_d16_hi v112, v113 offset:10032
	v_cvt_pk_bf16_f32 v113, v124, v125
	ds_write_b16 v112, v113 offset:12672
	ds_write_b16_d16_hi v112, v113 offset:13200
	v_cvt_pk_bf16_f32 v113, v126, v127
	ds_write_b16 v112, v113 offset:13728
	ds_write_b16_d16_hi v112, v113 offset:14256
	ds_write_b16 v112, v96 offset:64
	ds_write_b16_d16_hi v112, v96 offset:592
	v_cvt_pk_bf16_f32 v96, v98, v99
	ds_write_b16 v112, v96 offset:1120
	ds_write_b16_d16_hi v112, v96 offset:1648
	v_cvt_pk_bf16_f32 v96, v100, v101
	ds_write_b16 v112, v96 offset:4288
	ds_write_b16_d16_hi v112, v96 offset:4816
	v_cvt_pk_bf16_f32 v96, v102, v103
	ds_write_b16 v112, v96 offset:5344
	ds_write_b16_d16_hi v112, v96 offset:5872
	v_cvt_pk_bf16_f32 v96, v104, v105
	v_mfma_f32_32x32x16_bf16 v[48:63], v[220:223], v[148:151], v[48:63]
; DI unsigned pk2(float a, float b) { fl2_t f = {a, b}; bf2_t r = __builtin_convertvector(f, bf2_t); return __builtin_bit_cast(unsigned, r); }
; #define RAW_BARRIER() do { asm volatile("s_waitcnt lgkmcnt(0)" ::: "memory"); __builtin_amdgcn_s_barrier(); } while (0)
; template <typename FA, typename FB, typename FE>
; DI void gemm_tile(char* lds, int K, int astride, int bstride, FA arow, FB brow, FE epi) {
;     ...
;   RAW_BARRIER();
;   bfr* Cs = (bfr*)lds;
; #pragma unroll
;   for (int mt = 0; mt < 2; ++mt)
; #pragma unroll
;     for (int nt = 0; nt < 4; ++nt)
; #pragma unroll
;       for (int i = 0; i < 16; i += 2) {
;         const int row = wm * 64 + mt * 32 + (i & 3) + 8 * (i >> 2) + 4 * h8;
;         const unsigned pr = pk2(acc[mt][nt][i], acc[mt][nt][i + 1]);
;         Cs[row * CSS + wn * 128 + nt * 32 + r] = (bfr)(pr & 0xffffu);
;         Cs[(row + 1) * CSS + wn * 128 + nt * 32 + r] = (bfr)(pr >> 16);
;       }
;   __syncthreads();
	ds_write_b16 v112, v96 offset:8512
	ds_write_b16_d16_hi v112, v96 offset:9040
	v_cvt_pk_bf16_f32 v96, v106, v107
	ds_write_b16 v112, v96 offset:9568
	ds_write_b16_d16_hi v112, v96 offset:10096
	v_cvt_pk_bf16_f32 v96, v108, v109
	ds_write_b16 v112, v96 offset:12736
	ds_write_b16_d16_hi v112, v96 offset:13264
	v_cvt_pk_bf16_f32 v96, v110, v111
	v_cvt_pk_bf16_f32 v80, v80, v81
	ds_write_b16 v112, v96 offset:13792
	ds_write_b16_d16_hi v112, v96 offset:14320
	ds_write_b16 v112, v80 offset:128
	ds_write_b16_d16_hi v112, v80 offset:656
	v_cvt_pk_bf16_f32 v80, v82, v83
	ds_write_b16 v112, v80 offset:1184
	ds_write_b16_d16_hi v112, v80 offset:1712
	v_cvt_pk_bf16_f32 v80, v84, v85
	ds_write_b16 v112, v80 offset:4352
	ds_write_b16_d16_hi v112, v80 offset:4880
	v_cvt_pk_bf16_f32 v80, v86, v87
	ds_write_b16 v112, v80 offset:5408
	ds_write_b16_d16_hi v112, v80 offset:5936
	v_cvt_pk_bf16_f32 v80, v88, v89
	v_mfma_f32_32x32x16_bf16 v[32:47], v[220:223], v[180:183], v[32:47]
	ds_write_b16 v112, v80 offset:8576
	ds_write_b16_d16_hi v112, v80 offset:9104
	v_cvt_pk_bf16_f32 v80, v90, v91
	ds_write_b16 v112, v80 offset:9632
	ds_write_b16_d16_hi v112, v80 offset:10160
	v_cvt_pk_bf16_f32 v80, v92, v93
	ds_write_b16 v112, v80 offset:12800
	ds_write_b16_d16_hi v112, v80 offset:13328
	v_cvt_pk_bf16_f32 v80, v94, v95
	v_cvt_pk_bf16_f32 v64, v64, v65
	v_mfma_f32_32x32x16_bf16 v[48:63], v[164:167], v[160:163], v[48:63]
	ds_write_b16 v112, v80 offset:13856
	ds_write_b16_d16_hi v112, v80 offset:14384
	ds_write_b16 v112, v64 offset:192
	ds_write_b16_d16_hi v112, v64 offset:720
	v_cvt_pk_bf16_f32 v64, v66, v67
	ds_write_b16 v112, v64 offset:1248
	ds_write_b16_d16_hi v112, v64 offset:1776
	v_cvt_pk_bf16_f32 v64, v68, v69
	ds_write_b16 v112, v64 offset:4416
	ds_write_b16_d16_hi v112, v64 offset:4944
	v_cvt_pk_bf16_f32 v64, v70, v71
	ds_write_b16 v112, v64 offset:5472
	ds_write_b16_d16_hi v112, v64 offset:6000
	v_cvt_pk_bf16_f32 v64, v72, v73
	v_mfma_f32_32x32x16_bf16 v[16:31], v[220:223], v[176:179], v[16:31]
	ds_write_b16 v112, v64 offset:8640
	ds_write_b16_d16_hi v112, v64 offset:9168
	v_cvt_pk_bf16_f32 v64, v74, v75
	ds_write_b16 v112, v64 offset:9696
	ds_write_b16_d16_hi v112, v64 offset:10224
	v_cvt_pk_bf16_f32 v64, v76, v77
	ds_write_b16 v112, v64 offset:12864
	ds_write_b16_d16_hi v112, v64 offset:13392
	v_cvt_pk_bf16_f32 v64, v78, v79
	v_cvt_pk_bf16_f32 v48, v48, v49
	v_mfma_f32_32x32x16_bf16 v[32:47], v[164:167], v[156:159], v[32:47]
	ds_write_b16 v112, v64 offset:13920
	ds_write_b16_d16_hi v112, v64 offset:14448
	ds_write_b16 v112, v48 offset:16896
	ds_write_b16_d16_hi v112, v48 offset:17424
	v_cvt_pk_bf16_f32 v48, v50, v51
	ds_write_b16 v112, v48 offset:17952
	ds_write_b16_d16_hi v112, v48 offset:18480
	v_cvt_pk_bf16_f32 v48, v52, v53
	ds_write_b16 v112, v48 offset:21120
	ds_write_b16_d16_hi v112, v48 offset:21648
	v_cvt_pk_bf16_f32 v48, v54, v55
	ds_write_b16 v112, v48 offset:22176
	ds_write_b16_d16_hi v112, v48 offset:22704
	v_cvt_pk_bf16_f32 v48, v56, v57
	ds_write_b16 v112, v48 offset:25344
	ds_write_b16_d16_hi v112, v48 offset:25872
	v_cvt_pk_bf16_f32 v48, v58, v59
	v_mfma_f32_32x32x16_bf16 v[16:31], v[164:167], v[140:143], v[16:31]
	ds_write_b16 v112, v48 offset:26400
	ds_write_b16_d16_hi v112, v48 offset:26928
	v_cvt_pk_bf16_f32 v48, v60, v61
	ds_write_b16 v112, v48 offset:29568
	ds_write_b16_d16_hi v112, v48 offset:30096
	v_cvt_pk_bf16_f32 v48, v62, v63
	v_cvt_pk_bf16_f32 v32, v32, v33
	ds_write_b16 v112, v48 offset:30624
	ds_write_b16_d16_hi v112, v48 offset:31152
	ds_write_b16 v112, v32 offset:16960
	ds_write_b16_d16_hi v112, v32 offset:17488
	v_cvt_pk_bf16_f32 v32, v34, v35
	ds_write_b16 v112, v32 offset:18016
	ds_write_b16_d16_hi v112, v32 offset:18544
	v_cvt_pk_bf16_f32 v32, v36, v37
	ds_write_b16 v112, v32 offset:21184
	ds_write_b16_d16_hi v112, v32 offset:21712
	v_cvt_pk_bf16_f32 v32, v38, v39
	ds_write_b16 v112, v32 offset:22240
	ds_write_b16_d16_hi v112, v32 offset:22768
	v_cvt_pk_bf16_f32 v32, v40, v41
	ds_write_b16 v112, v32 offset:25408
	ds_write_b16_d16_hi v112, v32 offset:25936
	v_cvt_pk_bf16_f32 v32, v42, v43
	ds_write_b16 v112, v32 offset:26464
	ds_write_b16_d16_hi v112, v32 offset:26992
	v_cvt_pk_bf16_f32 v32, v44, v45
	ds_write_b16 v112, v32 offset:29632
	ds_write_b16_d16_hi v112, v32 offset:30160
	v_cvt_pk_bf16_f32 v32, v46, v47
	v_cvt_pk_bf16_f32 v16, v16, v17
	ds_write_b16 v112, v32 offset:30688
	ds_write_b16_d16_hi v112, v32 offset:31216
	ds_write_b16 v112, v16 offset:17024
	ds_write_b16_d16_hi v112, v16 offset:17552
	v_cvt_pk_bf16_f32 v16, v18, v19
	ds_write_b16 v112, v16 offset:18080
	ds_write_b16_d16_hi v112, v16 offset:18608
	v_cvt_pk_bf16_f32 v16, v20, v21
	ds_write_b16 v112, v16 offset:21248
	ds_write_b16_d16_hi v112, v16 offset:21776
	v_cvt_pk_bf16_f32 v16, v22, v23
	ds_write_b16 v112, v16 offset:22304
	ds_write_b16_d16_hi v112, v16 offset:22832
	v_cvt_pk_bf16_f32 v16, v24, v25
	ds_write_b16 v112, v16 offset:25472
	ds_write_b16_d16_hi v112, v16 offset:26000
	v_cvt_pk_bf16_f32 v16, v26, v27
	ds_write_b16 v112, v16 offset:26528
	ds_write_b16_d16_hi v112, v16 offset:27056
	v_cvt_pk_bf16_f32 v16, v28, v29
	ds_write_b16 v112, v16 offset:29696
	ds_write_b16_d16_hi v112, v16 offset:30224
	v_cvt_pk_bf16_f32 v16, v30, v31
	v_cvt_pk_bf16_f32 v0, v0, v1
	ds_write_b16 v112, v16 offset:30752
	ds_write_b16_d16_hi v112, v16 offset:31280
	ds_write_b16 v112, v0 offset:17088
	ds_write_b16_d16_hi v112, v0 offset:17616
	v_cvt_pk_bf16_f32 v0, v2, v3
	ds_write_b16 v112, v0 offset:18144
	ds_write_b16_d16_hi v112, v0 offset:18672
	v_cvt_pk_bf16_f32 v0, v4, v5
	ds_write_b16 v112, v0 offset:21312
	ds_write_b16_d16_hi v112, v0 offset:21840
	v_cvt_pk_bf16_f32 v0, v6, v7
	ds_write_b16 v112, v0 offset:22368
	ds_write_b16_d16_hi v112, v0 offset:22896
	v_cvt_pk_bf16_f32 v0, v8, v9
	ds_write_b16 v112, v0 offset:25536
	ds_write_b16_d16_hi v112, v0 offset:26064
	v_cvt_pk_bf16_f32 v0, v10, v11
	ds_write_b16 v112, v0 offset:26592
	ds_write_b16_d16_hi v112, v0 offset:27120
	v_cvt_pk_bf16_f32 v0, v12, v13
	ds_write_b16 v112, v0 offset:29760
	ds_write_b16_d16_hi v112, v0 offset:30288
	v_cvt_pk_bf16_f32 v0, v14, v15
	ds_write_b16 v112, v0 offset:30816
	ds_write_b16_d16_hi v112, v0 offset:31344
	s_waitcnt vmcnt(0) lgkmcnt(0)
	s_barrier
; DI void phase_moe(const Params& p, char* lds, int mode) {
;     ...
;           float4 ov[16]; u32x2 yv[16]; float gt[16]; int tk[16];
; #pragma unroll
;           for (int ps = 0; ps < 16; ++ps) {
;             const int grow = half * 128 + ps * 8 + (tid >> 5);
;             tk[ps] = rowtok[grow];
;             gt[ps] = gate[(size_t)k * T + tk[ps]];
;             ov[ps] = *(const float4*)(p.out + (size_t)tk[ps] * D + col);
;             yv[ps] = *(const u32x2*)(Y0 + (size_t)tk[ps] * D + col);
;           }
	ds_read2_b32 v[168:169], v194 offset1:8
	v_or_b32_e32 v64, s0, v192
	v_ashrrev_i32_e32 v65, 31, v64
	v_lshl_add_u64 v[72:73], v[64:65], 1, s[42:43]
	ds_read2_b32 v[154:155], v194 offset0:16 offset1:24
	s_waitcnt lgkmcnt(1)
	v_ashrrev_i32_e32 v1, 31, v168
	v_mov_b32_e32 v0, v168
	v_lshl_add_u64 v[2:3], v[0:1], 2, s[44:45]
	v_lshlrev_b64 v[184:185], 12, v[0:1]
	v_lshlrev_b64 v[0:1], 11, v[0:1]
	v_lshl_add_u64 v[66:67], v[64:65], 2, s[46:47]
	v_lshl_add_u64 v[0:1], v[72:73], 0, v[0:1]
	global_load_dword v180, v[2:3], off
	v_lshl_add_u64 v[2:3], v[66:67], 0, v[184:185]
	global_load_dwordx2 v[182:183], v[0:1], off
	v_ashrrev_i32_e32 v1, 31, v169
	v_mov_b32_e32 v0, v169
	global_load_dwordx4 v[60:63], v[2:3], off
	v_lshl_add_u64 v[2:3], v[0:1], 2, s[44:45]
	v_lshlrev_b64 v[178:179], 12, v[0:1]
	v_lshlrev_b64 v[0:1], 11, v[0:1]
	v_lshl_add_u64 v[0:1], v[72:73], 0, v[0:1]
	global_load_dword v172, v[2:3], off
	v_lshl_add_u64 v[2:3], v[66:67], 0, v[178:179]
	global_load_dwordx2 v[174:175], v[0:1], off
	s_waitcnt lgkmcnt(0)
	v_ashrrev_i32_e32 v1, 31, v154
	v_mov_b32_e32 v0, v154
	global_load_dwordx4 v[56:59], v[2:3], off
	v_lshl_add_u64 v[2:3], v[0:1], 2, s[44:45]
	v_lshlrev_b64 v[176:177], 12, v[0:1]
	v_lshlrev_b64 v[0:1], 11, v[0:1]
	ds_read2_b32 v[140:141], v194 offset0:32 offset1:40
	v_lshl_add_u64 v[0:1], v[72:73], 0, v[0:1]
	global_load_dword v166, v[2:3], off
	v_lshl_add_u64 v[2:3], v[66:67], 0, v[176:177]
	global_load_dwordx2 v[170:171], v[0:1], off
	v_ashrrev_i32_e32 v1, 31, v155
	v_mov_b32_e32 v0, v155
	global_load_dwordx4 v[52:55], v[2:3], off
	v_lshl_add_u64 v[2:3], v[0:1], 2, s[44:45]
	v_lshlrev_b64 v[164:165], 12, v[0:1]
	v_lshlrev_b64 v[0:1], 11, v[0:1]
	v_lshl_add_u64 v[0:1], v[72:73], 0, v[0:1]
	global_load_dword v158, v[2:3], off
	v_lshl_add_u64 v[2:3], v[66:67], 0, v[164:165]
	global_load_dwordx2 v[160:161], v[0:1], off
	s_waitcnt lgkmcnt(0)
	v_ashrrev_i32_e32 v1, 31, v140
	v_mov_b32_e32 v0, v140
	global_load_dwordx4 v[48:51], v[2:3], off
	v_lshl_add_u64 v[2:3], v[0:1], 2, s[44:45]
	v_lshlrev_b64 v[162:163], 12, v[0:1]
	v_lshlrev_b64 v[0:1], 11, v[0:1]
	ds_read2_b32 v[120:121], v194 offset0:48 offset1:56
	v_lshl_add_u64 v[0:1], v[72:73], 0, v[0:1]
	global_load_dword v152, v[2:3], off
	v_lshl_add_u64 v[2:3], v[66:67], 0, v[162:163]
	global_load_dwordx2 v[156:157], v[0:1], off
	v_ashrrev_i32_e32 v1, 31, v141
	v_mov_b32_e32 v0, v141
	global_load_dwordx4 v[44:47], v[2:3], off
	v_lshl_add_u64 v[2:3], v[0:1], 2, s[44:45]
	v_lshlrev_b64 v[150:151], 12, v[0:1]
	v_lshlrev_b64 v[0:1], 11, v[0:1]
	v_lshl_add_u64 v[0:1], v[72:73], 0, v[0:1]
	global_load_dword v144, v[2:3], off
	v_lshl_add_u64 v[2:3], v[66:67], 0, v[150:151]
	global_load_dwordx2 v[146:147], v[0:1], off
	s_waitcnt lgkmcnt(0)
	v_ashrrev_i32_e32 v1, 31, v120
	v_mov_b32_e32 v0, v120
	global_load_dwordx4 v[40:43], v[2:3], off
	v_lshl_add_u64 v[2:3], v[0:1], 2, s[44:45]
	v_lshlrev_b64 v[148:149], 12, v[0:1]
	v_lshlrev_b64 v[0:1], 11, v[0:1]
	ds_read2_b32 v[106:107], v194 offset0:64 offset1:72
	v_lshl_add_u64 v[0:1], v[72:73], 0, v[0:1]
	global_load_dword v128, v[2:3], off
	v_lshl_add_u64 v[2:3], v[66:67], 0, v[148:149]
	global_load_dwordx2 v[142:143], v[0:1], off
	v_ashrrev_i32_e32 v1, 31, v121
	v_mov_b32_e32 v0, v121
	global_load_dwordx4 v[36:39], v[2:3], off
	v_lshl_add_u64 v[2:3], v[0:1], 2, s[44:45]
	v_lshlrev_b64 v[138:139], 12, v[0:1]
	v_lshlrev_b64 v[0:1], 11, v[0:1]
	v_lshl_add_u64 v[0:1], v[72:73], 0, v[0:1]
	global_load_dword v124, v[2:3], off
	v_lshl_add_u64 v[2:3], v[66:67], 0, v[138:139]
	global_load_dwordx2 v[126:127], v[0:1], off
	s_waitcnt lgkmcnt(0)
	v_ashrrev_i32_e32 v1, 31, v106
	v_mov_b32_e32 v0, v106
	global_load_dwordx4 v[32:35], v[2:3], off
	v_lshl_add_u64 v[2:3], v[0:1], 2, s[44:45]
	v_lshlrev_b64 v[136:137], 12, v[0:1]
	v_lshlrev_b64 v[0:1], 11, v[0:1]
	ds_read2_b32 v[92:93], v194 offset0:80 offset1:88
	v_lshl_add_u64 v[0:1], v[72:73], 0, v[0:1]
	global_load_dword v118, v[2:3], off
	v_lshl_add_u64 v[2:3], v[66:67], 0, v[136:137]
	global_load_dwordx2 v[122:123], v[0:1], off
	v_ashrrev_i32_e32 v1, 31, v107
	v_mov_b32_e32 v0, v107
	global_load_dwordx4 v[28:31], v[2:3], off
	v_lshl_add_u64 v[2:3], v[0:1], 2, s[44:45]
	v_lshlrev_b64 v[116:117], 12, v[0:1]
	v_lshlrev_b64 v[0:1], 11, v[0:1]
	v_lshl_add_u64 v[0:1], v[72:73], 0, v[0:1]
	global_load_dword v110, v[2:3], off
	v_lshl_add_u64 v[2:3], v[66:67], 0, v[116:117]
	global_load_dwordx2 v[112:113], v[0:1], off
	s_waitcnt lgkmcnt(0)
; DI void phase_moe(const Params& p, char* lds, int mode) {
;     ...
;           for (int ps = 0; ps < 16; ++ps) {
;             const int grow = half * 128 + ps * 8 + (tid >> 5);
;             tk[ps] = rowtok[grow];
;             gt[ps] = gate[(size_t)k * T + tk[ps]];
;             ov[ps] = *(const float4*)(p.out + (size_t)tk[ps] * D + col);
;             yv[ps] = *(const u32x2*)(Y0 + (size_t)tk[ps] * D + col);
;           }
;           asm volatile("" ::: "memory");
; #pragma unroll
;           for (int ps = 0; ps < 16; ++ps) {
;             const int row = ps * 8 + (tid >> 5);
;             if (r0 + half * 128 + row < n) {
;               int br, s_, S_; tok_info(tk[ps], br, s_, S_);
;               const float4 g2 = *(const float4*)(g2t + br * 256 + ch * 128 + c4);
;               float4 c = cs4(Cs, row, c4);
;               float4 o = ov[ps];
;               const float g = gt[ps];
;               o.x += g2.x * (__uint_as_float(yv[ps][0] << 16) + g * c.x);
;               o.y += g2.y * (__uint_as_float(yv[ps][0] & 0xffff0000u) + g * c.y);
;               o.z += g2.z * (__uint_as_float(yv[ps][1] << 16) + g * c.z);
;               o.w += g2.w * (__uint_as_float(yv[ps][1] & 0xffff0000u) + g * c.w);
;               *(float4*)(p.out + (size_t)tk[ps] * D + col) = o;
	v_ashrrev_i32_e32 v1, 31, v92
	v_mov_b32_e32 v0, v92
	global_load_dwordx4 v[24:27], v[2:3], off
	v_lshl_add_u64 v[2:3], v[0:1], 2, s[44:45]
	v_lshlrev_b64 v[114:115], 12, v[0:1]
	v_lshlrev_b64 v[0:1], 11, v[0:1]
	ds_read2_b32 v[78:79], v194 offset0:96 offset1:104
	v_lshl_add_u64 v[0:1], v[72:73], 0, v[0:1]
	global_load_dword v104, v[2:3], off
	v_lshl_add_u64 v[2:3], v[66:67], 0, v[114:115]
	global_load_dwordx2 v[108:109], v[0:1], off
	v_ashrrev_i32_e32 v1, 31, v93
	v_mov_b32_e32 v0, v93
	global_load_dwordx4 v[20:23], v[2:3], off
	v_lshl_add_u64 v[2:3], v[0:1], 2, s[44:45]
	v_lshlrev_b64 v[102:103], 12, v[0:1]
	v_lshlrev_b64 v[0:1], 11, v[0:1]
	v_lshl_add_u64 v[0:1], v[72:73], 0, v[0:1]
	global_load_dword v96, v[2:3], off
	v_lshl_add_u64 v[2:3], v[66:67], 0, v[102:103]
	global_load_dwordx2 v[98:99], v[0:1], off
	s_waitcnt lgkmcnt(0)
	v_ashrrev_i32_e32 v1, 31, v78
	v_mov_b32_e32 v0, v78
	global_load_dwordx4 v[16:19], v[2:3], off
	v_lshl_add_u64 v[2:3], v[0:1], 2, s[44:45]
	v_lshlrev_b64 v[100:101], 12, v[0:1]
	v_lshlrev_b64 v[0:1], 11, v[0:1]
	ds_read2_b32 v[68:69], v194 offset0:112 offset1:120
	v_lshl_add_u64 v[0:1], v[72:73], 0, v[0:1]
	global_load_dword v90, v[2:3], off
	v_lshl_add_u64 v[2:3], v[66:67], 0, v[100:101]
	global_load_dwordx2 v[94:95], v[0:1], off
	v_ashrrev_i32_e32 v1, 31, v79
	v_mov_b32_e32 v0, v79
	global_load_dwordx4 v[12:15], v[2:3], off
	v_lshl_add_u64 v[2:3], v[0:1], 2, s[44:45]
	v_lshlrev_b64 v[88:89], 12, v[0:1]
	v_lshlrev_b64 v[0:1], 11, v[0:1]
	v_lshl_add_u64 v[0:1], v[72:73], 0, v[0:1]
	global_load_dword v82, v[2:3], off
	v_lshl_add_u64 v[2:3], v[66:67], 0, v[88:89]
	global_load_dwordx2 v[84:85], v[0:1], off
	s_waitcnt lgkmcnt(0)
	v_ashrrev_i32_e32 v1, 31, v68
	v_mov_b32_e32 v0, v68
	global_load_dwordx4 v[8:11], v[2:3], off
	v_lshl_add_u64 v[2:3], v[0:1], 2, s[44:45]
	v_lshlrev_b64 v[86:87], 12, v[0:1]
	v_lshlrev_b64 v[0:1], 11, v[0:1]
	v_lshl_add_u64 v[0:1], v[72:73], 0, v[0:1]
	v_ashrrev_i32_e32 v221, 31, v69
	v_mov_b32_e32 v220, v69
	global_load_dwordx2 v[80:81], v[0:1], off
	v_lshl_add_u64 v[0:1], v[220:221], 2, s[44:45]
	v_lshlrev_b64 v[74:75], 12, v[220:221]
	v_lshlrev_b64 v[220:221], 11, v[220:221]
	global_load_dword v76, v[2:3], off
	v_lshl_add_u64 v[2:3], v[66:67], 0, v[86:87]
	global_load_dword v70, v[0:1], off
	v_lshl_add_u64 v[0:1], v[66:67], 0, v[74:75]
	v_lshl_add_u64 v[72:73], v[72:73], 0, v[220:221]
	global_load_dwordx4 v[4:7], v[2:3], off
	v_add_u32_e32 v71, v153, v193
	global_load_dwordx4 v[0:3], v[0:1], off
	v_cmp_lt_i32_e32 vcc, v71, v145
	global_load_dwordx2 v[72:73], v[72:73], off
	s_and_saveexec_b64 s[4:5], vcc
	s_cbranch_execz .LBB0_430
	v_add_u32_e32 v71, 0xffff0000, v168
	v_lshrrev_b32_e32 v71, 14, v71
	v_add_u32_e32 v71, 16, v71
	v_ashrrev_i32_e32 v77, 12, v168
	v_cmp_gt_i32_e64 s[0:1], s33, v168
	ds_read_b64 v[224:225], v196
	s_waitcnt vmcnt(46)
	v_lshlrev_b32_e32 v228, 16, v182
	v_cndmask_b32_e64 v71, v71, v77, s[0:1]
	v_lshl_add_u32 v71, v71, 10, v195
	ds_read_b128 v[220:223], v71
	s_waitcnt lgkmcnt(1)
	v_lshlrev_b32_e32 v226, 16, v224
	v_and_b32_e32 v227, 0xffff0000, v224
	v_and_b32_e32 v229, 0xffff0000, v182
	v_pk_fma_f32 v[226:227], v[180:181], v[226:227], v[228:229] op_sel_hi:[0,1,1]
	s_waitcnt vmcnt(45) lgkmcnt(0)
	v_pk_fma_f32 v[60:61], v[220:221], v[226:227], v[60:61]
	v_lshlrev_b32_e32 v220, 16, v225
	v_and_b32_e32 v221, 0xffff0000, v225
	v_lshlrev_b32_e32 v182, 16, v183
	v_and_b32_e32 v183, 0xffff0000, v183
	v_lshl_add_u64 v[184:185], s[46:47], 0, v[184:185]
	v_pk_fma_f32 v[180:181], v[180:181], v[220:221], v[182:183] op_sel_hi:[0,1,1]
	v_lshl_add_u64 v[184:185], v[64:65], 2, v[184:185]
	v_pk_fma_f32 v[62:63], v[222:223], v[180:181], v[62:63]
	global_store_dwordx4 v[184:185], v[60:63], off
